# P2->P3: workgroups enter the scan once the 192 operand-producing workgroups have arrived; each scan wave's first YRAW store waits for all workgroups to have left P2
# baseline (speedup 1.0000x reference)
; __device__ __forceinline__ unsigned xb_ld(unsigned* p) { return __hip_atomic_load(p, __ATOMIC_RELAXED, __HIP_MEMORY_SCOPE_AGENT); }
; __device__ __forceinline__ unsigned xb_add(unsigned* p, unsigned v) { return __hip_atomic_fetch_add(p, v, __ATOMIC_RELAXED, __HIP_MEMORY_SCOPE_AGENT); }
; __device__ __forceinline__ void xcd_barrier(const XB& b) {
;     __syncthreads();
;     if (threadIdx.x == 0) {
;         unsigned* bar = b.bar;
;         __builtin_amdgcn_fence(__ATOMIC_RELEASE, "agent");
;         asm volatile("s_waitcnt vmcnt(0)" ::: "memory");
;         const unsigned old = xb_add(&bar[XB_XSUB(b.x)], 1u);
;         const unsigned gen = old / b.nloc;
;         if (old + 1u == (gen + 1u) * b.nloc) {
;             const unsigned og = xb_add(&bar[XB_TOP], 1u);
;             const unsigned target = (og / b.nx + 1u) * b.nx;
;             if (og + 1u != target) while (xb_ld(&bar[XB_TOP]) < target) __builtin_amdgcn_s_sleep(1);
;             xb_add(&bar[XB_XGEN(b.x)], 1u);
;         } else {
;             while (xb_ld(&bar[XB_XGEN(b.x)]) == gen) __builtin_amdgcn_s_sleep(1);
;         }
;         __builtin_amdgcn_fence(__ATOMIC_ACQUIRE, "agent");
;         asm volatile("s_waitcnt vmcnt(0)" ::: "memory");
;     }
;     __syncthreads();
.Linvw_4:
	s_mov_b64 s[0:1], exec
	v_readlane_b32 s4, v253, 2
	v_readlane_b32 s5, v253, 3
	s_and_b64 s[4:5], s[0:1], s[4:5]
	s_mov_b64 exec, s[4:5]
	s_cbranch_execz .LBB0_308
	s_cmpk_lg_i32 s33, 0x100
	s_cbranch_scc1 .Lps_h_orig
	buffer_wbl2 sc1
	s_waitcnt vmcnt(0)
	v_mov_b32_e32 v4, 0x1b6f980
	v_mov_b32_e32 v5, 1
	global_atomic_add v4, v5, s[82:83]
	v_mov_b32_e32 v7, 0x1b6fa80
	s_cmpk_lt_u32 s2, 64
	s_cbranch_scc1 .Lps_h_poll
	global_atomic_add v7, v5, s[82:83]
.Lps_h_poll:
	global_load_dword v6, v7, s[82:83] sc1
	s_waitcnt vmcnt(0)
	v_readfirstlane_b32 s97, v6
	s_cmpk_lt_u32 s97, 0xc0
	s_cbranch_scc0 .LBB0_308
	s_sleep 1
	s_branch .Lps_h_poll
.Lps_h_orig:
	s_mov_b64 s[6:7], exec
	buffer_wbl2 sc1
	s_waitcnt vmcnt(0)
	s_waitcnt vmcnt(0)
	s_lshl_b32 s3, s89, 8
	v_readlane_b32 s4, v253, 0
	v_mbcnt_lo_u32_b32 v0, s6, 0
	v_readlane_b32 s5, v253, 1
	s_add_u32 s4, s4, s3
	v_mbcnt_hi_u32_b32 v0, s7, v0
	s_addc_u32 s5, s5, 0
	v_cmp_eq_u32_e32 vcc, 0, v0
	s_and_saveexec_b64 s[8:9], vcc
	s_cbranch_execz .LBB0_292
	s_bcnt1_i32_b64 s3, s[6:7]
	v_mov_b32_e32 v1, 0x1000
	v_mov_b32_e32 v2, s3
	global_atomic_add v1, v1, v2, s[4:5] sc0

; #define LAS __attribute__((address_space(3)))
; __device__ __forceinline__ void rwkv_scan_prompt(const Params& p, LAS unsigned char* lds, int bh, int rq) {
;     constexpr int TC = 32, NCH = SEQ / TC, NPIECE = TC * 48 / 256;
;     unsigned char* ws = p.ws;
;     LAS float* OPS = (LAS float*)lds;
;     LAS float* RKB = (LAS float*)(lds + 2 * TC * 6 * 64 * 4);
;     const int tid = threadIdx.x, lane = tid & 63, wave = tid >> 6;
;     const int b = bh >> 3, h = bh & 7, rowbase = b * SEQ;
;     const h16* OPSG = (const h16*)(ws + OFF_OPS16);
;     const float* RKS = (const float*)(ws + OFF_RKS);
;     float* YRAW = (float*)(ws + OFF_YRAW);
;     const int rr = lane >> 4, cg_ = lane & 15, rloc = (wave & 3) * 4 + rr;
;     const int ltid = tid - 256;
;     f32x4 S = {0.f, 0.f, 0.f, 0.f};
;     h16x8 pre[NPIECE]; float prk = 0.f;
;     auto issue_chunk = [&](int c) {
; #pragma unroll
;         for (int i = 0; i < NPIECE; ++i) {
;             const int piece = ltid + 256 * i, tk = piece / 48, q = piece % 48, vec = q >> 3, c8 = q & 7;
;             pre[i] = *(const h16x8*)(OPSG + (((size_t)(rowbase + c * TC + tk) * 8 + h) * 6 + vec) * 64 + c8 * 8);
;         }
;         if (ltid < TC) prk = RKS[(size_t)(rowbase + c * TC + ltid) * 8 + h];
;     };
;     auto store_chunk = [&](int buf) {
; #pragma unroll
;         for (int i = 0; i < NPIECE; ++i) {
;             const int piece = ltid + 256 * i, tk = piece / 48, q = piece % 48, vec = q >> 3, c8 = q & 7;
;             const h16x8 v = pre[i];
;             f32x4 a, bb;
; #pragma unroll
;             for (int j = 0; j < 4; ++j) { a[j] = (float)v[j]; bb[j] = (float)v[4 + j]; }
;             if (vec == 1) {
; #pragma unroll
;                 for (int j = 0; j < 4; ++j) { a[j] = __expf(a[j]); bb[j] = __expf(bb[j]); }
;             }
;             LAS float* d = OPS + ((buf * TC + tk) * 6 + vec) * 64 + c8 * 8;
;             *(LAS f32x4*)d = a; *(LAS f32x4*)(d + 4) = bb;
;         }
;         if (ltid < TC) RKB[buf * TC + ltid] = prk;
;     };
;     if (wave >= 4) { issue_chunk(0); store_chunk(0); issue_chunk(1); }
.LBB0_308:
	s_cmpk_lg_i32 s33, 0x100
	s_cselect_b32 s100, 1, 0
	s_or_b64 exec, exec, s[0:1]
	s_cmpk_lt_i32 s2, 0x100
	s_movk_i32 s0, 0x100
	s_cselect_b64 s[76:77], -1, 0
	s_cmpk_gt_i32 s2, 0xff
	v_lshlrev_b32_e32 v36, 2, v131
	v_cmp_eq_u32_e64 s[4:5], 15, v131
	v_cmp_eq_u32_e64 s[6:7], 0, v131
	v_cmp_eq_u32_e64 s[8:9], 1, v131
	v_cmp_eq_u32_e64 s[10:11], 2, v131
	v_cmp_eq_u32_e64 s[12:13], 3, v131
	v_cmp_eq_u32_e64 s[14:15], 4, v131
	v_cmp_eq_u32_e64 s[16:17], 5, v131
	v_cmp_eq_u32_e64 s[18:19], 6, v131
	v_cmp_eq_u32_e64 s[20:21], 7, v131
	v_cmp_eq_u32_e64 s[22:23], 8, v131
	v_cmp_eq_u32_e64 s[24:25], 9, v131
	v_cmp_eq_u32_e64 s[26:27], 10, v131
	v_cmp_eq_u32_e64 s[28:29], 11, v131
	v_cmp_eq_u32_e64 s[30:31], 12, v131
	v_cmp_eq_u32_e64 s[34:35], 13, v131
	v_cmp_eq_u32_e64 s[36:37], 14, v131
	v_lshlrev_b32_e32 v52, 4, v131
	s_barrier
	s_cbranch_scc1 .LBB0_360
	v_add_u16_e32 v3, 0x100, v132
	v_mul_u32_u24_e32 v4, 0x556, v3
	v_lshrrev_b32_e32 v57, 16, v4
	v_mul_lo_u16_e32 v4, 48, v57
	v_sub_u16_e32 v63, v3, v4
	v_lshlrev_b32_e32 v3, 3, v63
	v_and_b32_e32 v46, 56, v3
	v_add_u16_e32 v3, 0x200, v132
	v_mul_u32_u24_e32 v4, 0x556, v3
	v_lshrrev_b32_e32 v65, 16, v4
	v_subrev_co_u32_e32 v37, vcc, 0x100, v132
	v_cmp_gt_u32_e64 s[38:39], s0, v132
	s_mov_b32 s0, 0xaaab
	v_mul_lo_u16_e32 v4, 48, v65
	v_mul_u32_u24_sdwa v1, v37, s0 dst_sel:DWORD dst_unused:UNUSED_PAD src0_sel:WORD_0 src1_sel:DWORD
	v_sub_u16_e32 v67, v3, v4
	v_lshrrev_b32_e32 v47, 21, v1
	v_mul_u32_u24_e32 v2, 0x556, v132
	v_lshlrev_b32_e32 v3, 3, v67
	v_mul_lo_u16_e32 v1, 48, v47
	v_lshrrev_b32_e32 v51, 16, v2
	v_and_b32_e32 v50, 56, v3
	v_add_u16_e32 v3, 0x300, v132
	v_sub_u16_e32 v1, v37, v1
	v_mul_lo_u16_e32 v2, 48, v51
	v_mul_u32_u24_e32 v4, 0x556, v3
	v_lshrrev_b32_e32 v38, 3, v1
	v_lshlrev_b32_e32 v1, 3, v1
	v_sub_u16_e32 v2, v132, v2
	v_lshrrev_b32_e32 v108, 16, v4
	v_and_b32_e32 v1, 56, v1
	v_lshrrev_b32_e32 v42, 3, v2
	v_lshlrev_b32_e32 v2, 3, v2
	v_mul_lo_u16_e32 v4, 48, v108
	v_mul_u32_u24_e32 v5, 6, v47
	v_and_b32_e32 v2, 56, v2
	v_sub_u16_e32 v109, v3, v4
	v_add_lshl_u32 v5, v5, v38, 8
	v_lshlrev_b32_e32 v6, 2, v1
	s_movk_i32 s0, 0x556
	v_lshlrev_b32_e32 v3, 3, v109
	v_or_b32_e32 v4, 0x400, v132
	v_add3_u32 v111, 0, v5, v6
	v_mad_u32_u24 v5, v51, 6, v42
	v_lshl_add_u32 v112, v2, 2, 0
	v_lshrrev_b32_e32 v44, 3, v63
	v_and_b32_e32 v56, 56, v3
	v_mul_u32_u24_sdwa v3, v4, s0 dst_sel:DWORD dst_unused:UNUSED_PAD src0_sel:WORD_0 src1_sel:DWORD
	v_lshl_add_u32 v113, v5, 8, v112
	v_mul_u32_u24_e32 v5, 6, v57
	v_lshrrev_b32_e32 v110, 16, v3
	v_add_lshl_u32 v5, v5, v44, 8
	v_lshlrev_b32_e32 v6, 2, v46
	v_lshrrev_b32_e32 v48, 3, v67
	v_mul_lo_u16_e32 v3, 48, v110
	v_add3_u32 v114, 0, v5, v6
	v_mul_u32_u24_e32 v5, 6, v65
	v_sub_u16_e32 v3, v4, v3
	v_add_lshl_u32 v5, v5, v48, 8
	v_lshlrev_b32_e32 v6, 2, v50
	v_lshrrev_b32_e32 v54, 3, v109
	v_lshrrev_b32_e32 v58, 3, v3
	v_lshlrev_b32_e32 v3, 3, v3
	v_add3_u32 v115, 0, v5, v6
	v_mul_u32_u24_e32 v5, 6, v108
	v_and_b32_e32 v3, 56, v3
	v_add_lshl_u32 v5, v5, v54, 8
	v_lshlrev_b32_e32 v6, 2, v56
	v_add3_u32 v116, 0, v5, v6
	v_mad_u32_u24 v5, v110, 6, v58
	v_lshl_add_u32 v117, v3, 2, 0
	v_lshl_add_u32 v118, v5, 8, v117
	v_mul_i32_i24_e32 v5, 0x2aab, v37
	v_mov_b32_e32 v6, 3
	v_ashrrev_i16_sdwa v7, v6, v5 dst_sel:DWORD dst_unused:UNUSED_PAD src0_sel:DWORD src1_sel:WORD_1
	v_lshrrev_b32_e32 v5, 31, v5
	v_add_u16_e32 v127, v7, v5
	v_mul_lo_u16_e32 v5, 48, v127
	v_sub_u16_e32 v5, v37, v5
	v_ashrrev_i32_sdwa v60, v6, sext(v5) dst_sel:DWORD dst_unused:UNUSED_PAD src0_sel:DWORD src1_sel:WORD_0
	v_lshlrev_b32_sdwa v5, v6, sext(v5) dst_sel:DWORD dst_unused:UNUSED_PAD src0_sel:DWORD src1_sel:WORD_0
	v_or_b32_e32 v6, 0x100, v132
	v_mul_u32_u24_sdwa v7, v6, s0 dst_sel:DWORD dst_unused:UNUSED_PAD src0_sel:WORD_0 src1_sel:DWORD
	v_lshrrev_b32_e32 v137, 16, v7
	v_mul_lo_u16_e32 v7, 48, v137
	v_sub_u16_e32 v139, v6, v7
	v_lshlrev_b32_e32 v6, 3, v139
	v_and_b32_e32 v62, 56, v6
	v_or_b32_e32 v6, 0x200, v132
	v_mul_u32_u24_sdwa v7, v6, s0 dst_sel:DWORD dst_unused:UNUSED_PAD src0_sel:WORD_0 src1_sel:DWORD
	v_lshrrev_b32_e32 v141, 16, v7
	v_mul_lo_u16_e32 v7, 48, v141
	v_sub_u16_e32 v143, v6, v7
	v_mov_b32_e32 v41, 0
	v_lshlrev_b32_e32 v6, 3, v143
	v_lshlrev_b32_e32 v40, 1, v1
	v_and_b32_e32 v64, 56, v6
	v_or_b32_e32 v6, 0x300, v132
	v_lshl_add_u64 v[68:69], s[86:87], 0, v[40:41]
	v_lshlrev_b32_e32 v40, 1, v2
	v_mul_u32_u24_sdwa v7, v6, s0 dst_sel:DWORD dst_unused:UNUSED_PAD src0_sel:WORD_0 src1_sel:DWORD
	v_lshl_add_u64 v[70:71], s[86:87], 0, v[40:41]
	v_lshlrev_b32_e32 v40, 1, v46
	v_lshrrev_b32_e32 v145, 16, v7
	v_lshl_add_u64 v[72:73], s[86:87], 0, v[40:41]
	v_lshlrev_b32_e32 v40, 1, v50
	v_mul_lo_u16_e32 v7, 48, v145
	v_lshl_add_u64 v[74:75], s[86:87], 0, v[40:41]
	v_lshlrev_b32_e32 v40, 1, v56
	v_readlane_b32 s60, v253, 20
	s_mov_b32 s0, 0x5555556
	s_add_i32 s3, 0, 0x18000
	v_and_b32_e32 v5, 56, v5
	v_sub_u16_e32 v147, v6, v7
	v_lshl_add_u64 v[76:77], s[86:87], 0, v[40:41]
	v_lshlrev_b32_e32 v40, 1, v3
	v_mov_b32_e32 v53, v41
	v_readlane_b32 s74, v253, 34
	v_readlane_b32 s75, v253, 35
	v_mul_hi_u32 v1, v4, s0
	v_bfe_u32 v0, v132, 4, 4
	v_lshl_add_u32 v119, v37, 2, s3
	v_add_u32_e32 v126, s3, v36
	s_movk_i32 s3, 0x120
	v_lshlrev_b32_e32 v6, 3, v147
	s_add_u32 s84, s82, 0x1aec800
	v_lshl_add_u64 v[78:79], s[86:87], 0, v[40:41]
	v_lshlrev_b32_e32 v40, 1, v5
	v_lshl_add_u64 v[2:3], s[74:75], 0, v[52:53]
	s_mov_b64 s[58:59], 0x419c100
	v_or_b32_e32 v148, 64, v1
	v_mov_b32_e32 v1, 64
	v_mov_b32_e32 v39, v41
	v_mov_b32_e32 v43, v41
	v_mov_b32_e32 v45, v41
	v_mov_b32_e32 v49, v41
	v_mov_b32_e32 v55, v41
	v_mov_b32_e32 v59, v41
	v_cmp_gt_u32_e64 s[40:41], 32, v37
	v_cmp_ne_u32_e64 s[42:43], 1, v38
	s_mov_b32 s1, 0
	v_cmp_ne_u32_e64 s[44:45], 1, v42
	v_cmp_ne_u32_e64 s[46:47], 1, v44
	v_cmp_ne_u32_e64 s[48:49], 1, v48
	v_cmp_ne_u32_e64 s[50:51], 1, v54
	v_cmp_ne_u32_e64 s[52:53], 1, v58
	v_add_u32_e32 v120, 32, v47
	v_add_u32_e32 v121, 32, v57
	v_add_u32_e32 v122, 32, v65
	v_add_u32_e32 v123, 32, v108
	v_add_u32_e32 v124, 32, v110
	v_add_u32_e32 v125, 0xffffff20, v132
	v_cmp_ne_u32_e64 s[54:55], 1, v60
	v_lshl_add_u32 v129, v5, 2, 0
	v_cmp_gt_u32_e64 s[56:57], s3, v132
	v_ashrrev_i32_e32 v61, 31, v60
	v_mul_u32_u24_e32 v135, 0x600, v131
	v_and_b32_e32 v66, 56, v6
	s_addc_u32 s85, s83, 0
	v_lshl_add_u64 v[80:81], s[86:87], 0, v[40:41]
	v_lshl_add_u64 v[82:83], v[2:3], 0, s[58:59]
	v_add_u32_e32 v53, 0xffffff40, v132
	v_or_b32_e32 v149, 64, v51
	v_add_u32_sdwa v150, sext(v127), v1 dst_sel:DWORD dst_unused:UNUSED_PAD src0_sel:WORD_0 src1_sel:DWORD
	v_lshlrev_b32_e32 v84, 2, v0
	s_mov_b32 s3, s2
	v_readlane_b32 s61, v253, 21
	v_readlane_b32 s62, v253, 22
	v_readlane_b32 s63, v253, 23
	v_readlane_b32 s64, v253, 24
	v_readlane_b32 s65, v253, 25
	v_readlane_b32 s66, v253, 26
	v_readlane_b32 s67, v253, 27
	v_readlane_b32 s68, v253, 28
	v_readlane_b32 s69, v253, 29
	v_readlane_b32 s70, v253, 30
	v_readlane_b32 s71, v253, 31
	v_readlane_b32 s72, v253, 32
	v_readlane_b32 s73, v253, 33
	s_branch .LBB0_311

; #define LAS __attribute__((address_space(3)))
; __device__ __forceinline__ void rwkv_scan_prompt(const Params& p, LAS unsigned char* lds, int bh, int rq) {
;     ...
;             const LAS float* ob = OPS + buf * TC * 6 * 64;
;             f32x4 r4 = *(const LAS f32x4*)(ob + cg_ * 4), d4 = *(const LAS f32x4*)(ob + 64 + cg_ * 4), k4 = *(const LAS f32x4*)(ob + 128 + cg_ * 4),
;                   a4 = *(const LAS f32x4*)(ob + 256 + cg_ * 4), b4 = *(const LAS f32x4*)(ob + 320 + cg_ * 4);
;             float vv = ob[192 + rq * 16 + rloc];
;             f32x4 rp = r4;
; #pragma unroll
;             for (int tk = 0; tk < TC; ++tk) {
;                 f32x4 nr4 = r4, nd4 = d4, nk4 = k4, na4 = a4, nb4 = b4; float nvv = vv;
;                 if (tk < TC - 1) {
;                     const LAS float* o = ob + (tk + 1) * 6 * 64;
;                     nr4 = *(const LAS f32x4*)(o + cg_ * 4); nd4 = *(const LAS f32x4*)(o + 64 + cg_ * 4); nk4 = *(const LAS f32x4*)(o + 128 + cg_ * 4);
;                     na4 = *(const LAS f32x4*)(o + 256 + cg_ * 4); nb4 = *(const LAS f32x4*)(o + 320 + cg_ * 4);
;                     nvv = o[192 + rq * 16 + rloc];
;                 }
;                 __builtin_amdgcn_sched_barrier(0);
;                 typedef float f32x2_ __attribute__((ext_vector_type(2)));
;                 f32x2_ ta = (f32x2_){S[0], S[1]} * (f32x2_){a4[0], a4[1]}; ta = (f32x2_){S[2], S[3]} * (f32x2_){a4[2], a4[3]} + ta;
;                 f32x2_ ty = (f32x2_){S[0], S[1]} * (f32x2_){rp[0], rp[1]}; ty = (f32x2_){S[2], S[3]} * (f32x2_){rp[2], rp[3]} + ty;
;                 const f32x4 T = S * d4 + vv * k4;
;                 float sa = ta[0] + ta[1];
;                 float yp = ty[0] + ty[1];
;                 sa = dpp_add<0xB1>(sa); yp = dpp_add<0xB1>(yp);
;                 sa = dpp_add<0x4E>(sa); yp = dpp_add<0x4E>(yp);
;                 sa = dpp_add<0x124>(sa); yp = dpp_add<0x124>(yp);
;                 sa = dpp_add<0x128>(sa); yp = dpp_add<0x128>(yp);
;                 if (tk > 0) yk[(tk - 1) >> 4] = (cg_ == ((tk - 1) & 15)) ? yp : yk[(tk - 1) >> 4];
;                 S = sa * b4 + T;
;                 rp = r4;
;                 r4 = nr4; d4 = nd4; k4 = nk4; a4 = na4; b4 = nb4; vv = nvv;
;             }
.LBB0_336:
	s_and_b32 s95, s73, 1
	s_and_saveexec_b64 s[74:75], s[38:39]
	s_xor_b64 s[74:75], exec, s[74:75]
	s_cbranch_execz .LBB0_338
	s_mul_i32 s78, s95, 0xc000
	s_add_i32 s78, s78, 0
	v_lshl_add_u32 v28, v36, 2, s78
	v_lshl_add_u32 v29, v154, 2, s78
	ds_read_b128 v[30:33], v28
	ds_read_b128 v[160:163], v28 offset:256
	ds_read_b128 v[164:167], v28 offset:512
	ds_read_b128 v[168:171], v28 offset:1024
	ds_read2st64_b32 v[34:35], v29 offset0:3 offset1:9
	ds_read_b128 v[172:175], v28 offset:1280
	ds_read_b128 v[176:179], v28 offset:1536
	ds_read_b128 v[180:183], v28 offset:1792
	ds_read_b128 v[184:187], v28 offset:2048
	ds_read_b128 v[188:191], v28 offset:2560
	ds_read_b128 v[192:195], v28 offset:2816
	s_waitcnt lgkmcnt(7)
	v_pk_mul_f32 v[170:171], v[26:27], v[170:171]
	s_waitcnt lgkmcnt(6)
	v_pk_mul_f32 v[164:165], v[164:165], v[34:35] op_sel_hi:[1,0]
	v_pk_fma_f32 v[168:169], v[24:25], v[168:169], v[170:171]
	v_pk_mul_f32 v[166:167], v[166:167], v[34:35] op_sel_hi:[1,0]
	v_add_f32_e32 v168, v168, v169
	v_pk_fma_f32 v[26:27], v[26:27], v[162:163], v[166:167]
	v_pk_fma_f32 v[24:25], v[24:25], v[160:161], v[164:165]
	v_add_f32_dpp v168, v168, v168 quad_perm:[1,0,3,2] row_mask:0xf bank_mask:0xf bound_ctrl:1
	s_nop 1
	v_add_f32_dpp v168, v168, v168 quad_perm:[2,3,0,1] row_mask:0xf bank_mask:0xf bound_ctrl:1
	s_nop 1
	v_add_f32_dpp v168, v168, v168 row_ror:4 row_mask:0xf bank_mask:0xf bound_ctrl:1
	s_nop 1
	v_add_f32_dpp v168, v168, v168 row_ror:8 row_mask:0xf bank_mask:0xf bound_ctrl:1
	s_waitcnt lgkmcnt(5)
	v_pk_fma_f32 v[196:197], v[172:173], v[168:169], v[24:25] op_sel_hi:[1,0,1]
	v_pk_fma_f32 v[198:199], v[174:175], v[168:169], v[26:27] op_sel_hi:[1,0,1]
	ds_read_b128 v[24:27], v28 offset:3072
	ds_read_b128 v[160:163], v28 offset:3328
	ds_read_b128 v[164:167], v28 offset:3584
	ds_read_b128 v[168:171], v28 offset:4096
	ds_read_b128 v[172:175], v28 offset:4352
	ds_read_b32 v34, v29 offset:3840
	s_waitcnt lgkmcnt(7)
	v_pk_mul_f32 v[190:191], v[190:191], v[198:199]
	v_pk_mul_f32 v[32:33], v[32:33], v[198:199]
	v_pk_fma_f32 v[188:189], v[188:189], v[196:197], v[190:191]
	v_pk_fma_f32 v[30:31], v[30:31], v[196:197], v[32:33]
	v_pk_mul_f32 v[32:33], v[180:181], v[196:197]
	v_pk_mul_f32 v[180:181], v[182:183], v[198:199]
	v_mov_b32_e32 v182, v35
	v_add_f32_e32 v35, v188, v189
	v_add_f32_e32 v30, v30, v31
	v_pk_fma_f32 v[180:181], v[186:187], v[182:183], v[180:181] op_sel_hi:[1,0,1]
	v_add_f32_dpp v31, v35, v35 quad_perm:[1,0,3,2] row_mask:0xf bank_mask:0xf bound_ctrl:1
	v_add_f32_dpp v30, v30, v30 quad_perm:[1,0,3,2] row_mask:0xf bank_mask:0xf bound_ctrl:1
	v_pk_fma_f32 v[32:33], v[184:185], v[182:183], v[32:33] op_sel_hi:[1,0,1]
	v_add_f32_dpp v31, v31, v31 quad_perm:[2,3,0,1] row_mask:0xf bank_mask:0xf bound_ctrl:1
	v_add_f32_dpp v30, v30, v30 quad_perm:[2,3,0,1] row_mask:0xf bank_mask:0xf bound_ctrl:1
	s_nop 0
	v_add_f32_dpp v31, v31, v31 row_ror:4 row_mask:0xf bank_mask:0xf bound_ctrl:1
	v_add_f32_dpp v35, v30, v30 row_ror:4 row_mask:0xf bank_mask:0xf bound_ctrl:1
	s_nop 0
	v_add_f32_dpp v30, v31, v31 row_ror:8 row_mask:0xf bank_mask:0xf bound_ctrl:1
	v_add_f32_dpp v31, v35, v35 row_ror:8 row_mask:0xf bank_mask:0xf bound_ctrl:1
	v_cndmask_b32_e64 v201, 0, v31, s[6:7]
	s_waitcnt lgkmcnt(6)
	v_pk_fma_f32 v[196:197], v[192:193], v[30:31], v[32:33] op_sel_hi:[1,0,1]
	v_pk_fma_f32 v[198:199], v[194:195], v[30:31], v[180:181] op_sel_hi:[1,0,1]
	ds_read_b128 v[30:33], v28 offset:4608
	ds_read_b128 v[180:183], v28 offset:4864
	ds_read_b128 v[184:187], v28 offset:5120
	ds_read_b128 v[188:191], v28 offset:5632
	ds_read_b128 v[192:195], v28 offset:5888
	ds_read_b32 v200, v29 offset:5376
	s_waitcnt lgkmcnt(8)
	v_pk_mul_f32 v[170:171], v[170:171], v[198:199]
	v_pk_mul_f32 v[160:161], v[160:161], v[196:197]
	v_pk_fma_f32 v[168:169], v[168:169], v[196:197], v[170:171]
	v_pk_mul_f32 v[170:171], v[178:179], v[198:199]
	v_pk_mul_f32 v[162:163], v[162:163], v[198:199]
	v_pk_fma_f32 v[170:171], v[176:177], v[196:197], v[170:171]
	s_waitcnt lgkmcnt(6)
	v_pk_fma_f32 v[162:163], v[166:167], v[34:35], v[162:163] op_sel_hi:[1,0,1]
	v_pk_fma_f32 v[34:35], v[164:165], v[34:35], v[160:161] op_sel_hi:[1,0,1]
	v_add_f32_e32 v160, v168, v169
	v_add_f32_e32 v161, v170, v171
	s_nop 0
	v_add_f32_dpp v160, v160, v160 quad_perm:[1,0,3,2] row_mask:0xf bank_mask:0xf bound_ctrl:1
	v_add_f32_dpp v161, v161, v161 quad_perm:[1,0,3,2] row_mask:0xf bank_mask:0xf bound_ctrl:1
	s_nop 0
	v_add_f32_dpp v160, v160, v160 quad_perm:[2,3,0,1] row_mask:0xf bank_mask:0xf bound_ctrl:1
	v_add_f32_dpp v161, v161, v161 quad_perm:[2,3,0,1] row_mask:0xf bank_mask:0xf bound_ctrl:1
	s_nop 0
	v_add_f32_dpp v160, v160, v160 row_ror:4 row_mask:0xf bank_mask:0xf bound_ctrl:1
	v_add_f32_dpp v161, v161, v161 row_ror:4 row_mask:0xf bank_mask:0xf bound_ctrl:1
	s_nop 0
	v_add_f32_dpp v160, v160, v160 row_ror:8 row_mask:0xf bank_mask:0xf bound_ctrl:1
	v_add_f32_dpp v161, v161, v161 row_ror:8 row_mask:0xf bank_mask:0xf bound_ctrl:1
	v_cndmask_b32_e64 v199, v201, v161, s[8:9]
	v_pk_fma_f32 v[34:35], v[172:173], v[160:161], v[34:35] op_sel_hi:[1,0,1]
	v_pk_fma_f32 v[196:197], v[174:175], v[160:161], v[162:163] op_sel_hi:[1,0,1]
	ds_read_b128 v[160:163], v28 offset:6144
	ds_read_b128 v[164:167], v28 offset:6400
	ds_read_b128 v[168:171], v28 offset:6656
	ds_read_b128 v[172:175], v28 offset:7168
	ds_read_b128 v[176:179], v28 offset:7424
	ds_read_b32 v198, v29 offset:6912
	s_waitcnt lgkmcnt(8)
; #define LAS __attribute__((address_space(3)))
; __device__ __forceinline__ void rwkv_scan_prompt(const Params& p, LAS unsigned char* lds, int bh, int rq) {
;     ...
;             for (int tk = 0; tk < TC; ++tk) {
;                 f32x4 nr4 = r4, nd4 = d4, nk4 = k4, na4 = a4, nb4 = b4; float nvv = vv;
;                 if (tk < TC - 1) {
;                     const LAS float* o = ob + (tk + 1) * 6 * 64;
;                     nr4 = *(const LAS f32x4*)(o + cg_ * 4); nd4 = *(const LAS f32x4*)(o + 64 + cg_ * 4); nk4 = *(const LAS f32x4*)(o + 128 + cg_ * 4);
;                     na4 = *(const LAS f32x4*)(o + 256 + cg_ * 4); nb4 = *(const LAS f32x4*)(o + 320 + cg_ * 4);
;                     nvv = o[192 + rq * 16 + rloc];
;                 }
;                 __builtin_amdgcn_sched_barrier(0);
;                 typedef float f32x2_ __attribute__((ext_vector_type(2)));
;                 f32x2_ ta = (f32x2_){S[0], S[1]} * (f32x2_){a4[0], a4[1]}; ta = (f32x2_){S[2], S[3]} * (f32x2_){a4[2], a4[3]} + ta;
;                 f32x2_ ty = (f32x2_){S[0], S[1]} * (f32x2_){rp[0], rp[1]}; ty = (f32x2_){S[2], S[3]} * (f32x2_){rp[2], rp[3]} + ty;
;                 const f32x4 T = S * d4 + vv * k4;
;                 float sa = ta[0] + ta[1];
;                 float yp = ty[0] + ty[1];
;                 sa = dpp_add<0xB1>(sa); yp = dpp_add<0xB1>(yp);
;                 sa = dpp_add<0x4E>(sa); yp = dpp_add<0x4E>(yp);
;                 sa = dpp_add<0x124>(sa); yp = dpp_add<0x124>(yp);
;                 sa = dpp_add<0x128>(sa); yp = dpp_add<0x128>(yp);
;                 if (tk > 0) yk[(tk - 1) >> 4] = (cg_ == ((tk - 1) & 15)) ? yp : yk[(tk - 1) >> 4];
;                 S = sa * b4 + T;
;                 rp = r4;
;                 r4 = nr4; d4 = nd4; k4 = nk4; a4 = na4; b4 = nb4; vv = nvv;
;             }
	v_pk_mul_f32 v[190:191], v[190:191], v[196:197]
	v_pk_mul_f32 v[26:27], v[26:27], v[196:197]
	v_pk_fma_f32 v[188:189], v[188:189], v[34:35], v[190:191]
	v_pk_fma_f32 v[24:25], v[24:25], v[34:35], v[26:27]
	v_pk_mul_f32 v[26:27], v[180:181], v[34:35]
	v_add_f32_e32 v180, v188, v189
	v_add_f32_e32 v24, v24, v25
	v_pk_mul_f32 v[34:35], v[182:183], v[196:197]
	v_add_f32_dpp v25, v180, v180 quad_perm:[1,0,3,2] row_mask:0xf bank_mask:0xf bound_ctrl:1
	v_add_f32_dpp v24, v24, v24 quad_perm:[1,0,3,2] row_mask:0xf bank_mask:0xf bound_ctrl:1
	s_waitcnt lgkmcnt(6)
	v_pk_fma_f32 v[34:35], v[186:187], v[200:201], v[34:35] op_sel_hi:[1,0,1]
	v_add_f32_dpp v25, v25, v25 quad_perm:[2,3,0,1] row_mask:0xf bank_mask:0xf bound_ctrl:1
	v_add_f32_dpp v24, v24, v24 quad_perm:[2,3,0,1] row_mask:0xf bank_mask:0xf bound_ctrl:1
	v_pk_fma_f32 v[26:27], v[184:185], v[200:201], v[26:27] op_sel_hi:[1,0,1]
	v_add_f32_dpp v25, v25, v25 row_ror:4 row_mask:0xf bank_mask:0xf bound_ctrl:1
	v_add_f32_dpp v180, v24, v24 row_ror:4 row_mask:0xf bank_mask:0xf bound_ctrl:1
	s_nop 0
	v_add_f32_dpp v24, v25, v25 row_ror:8 row_mask:0xf bank_mask:0xf bound_ctrl:1
	v_add_f32_dpp v25, v180, v180 row_ror:8 row_mask:0xf bank_mask:0xf bound_ctrl:1
	v_cndmask_b32_e64 v199, v199, v25, s[10:11]
	v_pk_fma_f32 v[196:197], v[192:193], v[24:25], v[26:27] op_sel_hi:[1,0,1]
	v_pk_fma_f32 v[34:35], v[194:195], v[24:25], v[34:35] op_sel_hi:[1,0,1]
	ds_read_b128 v[24:27], v28 offset:7680
	ds_read_b128 v[180:183], v28 offset:7936
	ds_read_b128 v[184:187], v28 offset:8192
	ds_read_b128 v[188:191], v28 offset:8704
	ds_read_b128 v[192:195], v28 offset:8960
	ds_read_b32 v200, v29 offset:8448
	s_waitcnt lgkmcnt(8)
	v_pk_mul_f32 v[174:175], v[174:175], v[34:35]
	v_pk_mul_f32 v[32:33], v[32:33], v[34:35]
	v_pk_fma_f32 v[172:173], v[172:173], v[196:197], v[174:175]
	v_pk_fma_f32 v[30:31], v[30:31], v[196:197], v[32:33]
	v_pk_mul_f32 v[32:33], v[164:165], v[196:197]
	v_add_f32_e32 v164, v172, v173
	v_add_f32_e32 v30, v30, v31
	v_pk_mul_f32 v[34:35], v[166:167], v[34:35]
	v_add_f32_dpp v31, v164, v164 quad_perm:[1,0,3,2] row_mask:0xf bank_mask:0xf bound_ctrl:1
	v_add_f32_dpp v30, v30, v30 quad_perm:[1,0,3,2] row_mask:0xf bank_mask:0xf bound_ctrl:1
	s_waitcnt lgkmcnt(6)
	v_pk_fma_f32 v[34:35], v[170:171], v[198:199], v[34:35] op_sel_hi:[1,0,1]
	v_add_f32_dpp v31, v31, v31 quad_perm:[2,3,0,1] row_mask:0xf bank_mask:0xf bound_ctrl:1
	v_add_f32_dpp v30, v30, v30 quad_perm:[2,3,0,1] row_mask:0xf bank_mask:0xf bound_ctrl:1
	v_pk_fma_f32 v[32:33], v[168:169], v[198:199], v[32:33] op_sel_hi:[1,0,1]
	v_add_f32_dpp v31, v31, v31 row_ror:4 row_mask:0xf bank_mask:0xf bound_ctrl:1
	v_add_f32_dpp v164, v30, v30 row_ror:4 row_mask:0xf bank_mask:0xf bound_ctrl:1
	s_nop 0
	v_add_f32_dpp v30, v31, v31 row_ror:8 row_mask:0xf bank_mask:0xf bound_ctrl:1
	v_add_f32_dpp v31, v164, v164 row_ror:8 row_mask:0xf bank_mask:0xf bound_ctrl:1
	v_cndmask_b32_e64 v199, v199, v31, s[12:13]
	v_pk_fma_f32 v[196:197], v[176:177], v[30:31], v[32:33] op_sel_hi:[1,0,1]
	v_pk_fma_f32 v[34:35], v[178:179], v[30:31], v[34:35] op_sel_hi:[1,0,1]
	ds_read_b128 v[30:33], v28 offset:9216
	ds_read_b128 v[164:167], v28 offset:9472
	ds_read_b128 v[168:171], v28 offset:9728
	ds_read_b128 v[172:175], v28 offset:10240
	ds_read_b128 v[176:179], v28 offset:10496
	ds_read_b32 v198, v29 offset:9984
	s_waitcnt lgkmcnt(8)
	v_pk_mul_f32 v[190:191], v[190:191], v[34:35]
	v_pk_mul_f32 v[162:163], v[162:163], v[34:35]
	v_pk_fma_f32 v[188:189], v[188:189], v[196:197], v[190:191]
	v_pk_fma_f32 v[160:161], v[160:161], v[196:197], v[162:163]
	v_pk_mul_f32 v[162:163], v[180:181], v[196:197]
	v_add_f32_e32 v180, v188, v189
	v_add_f32_e32 v160, v160, v161
	v_pk_mul_f32 v[34:35], v[182:183], v[34:35]
	v_add_f32_dpp v161, v180, v180 quad_perm:[1,0,3,2] row_mask:0xf bank_mask:0xf bound_ctrl:1
	v_add_f32_dpp v160, v160, v160 quad_perm:[1,0,3,2] row_mask:0xf bank_mask:0xf bound_ctrl:1
	s_waitcnt lgkmcnt(6)
	v_pk_fma_f32 v[34:35], v[186:187], v[200:201], v[34:35] op_sel_hi:[1,0,1]
	v_add_f32_dpp v161, v161, v161 quad_perm:[2,3,0,1] row_mask:0xf bank_mask:0xf bound_ctrl:1
	v_add_f32_dpp v160, v160, v160 quad_perm:[2,3,0,1] row_mask:0xf bank_mask:0xf bound_ctrl:1
	v_pk_fma_f32 v[162:163], v[184:185], v[200:201], v[162:163] op_sel_hi:[1,0,1]
	v_add_f32_dpp v161, v161, v161 row_ror:4 row_mask:0xf bank_mask:0xf bound_ctrl:1
	v_add_f32_dpp v180, v160, v160 row_ror:4 row_mask:0xf bank_mask:0xf bound_ctrl:1
	s_nop 0
	v_add_f32_dpp v160, v161, v161 row_ror:8 row_mask:0xf bank_mask:0xf bound_ctrl:1
	v_add_f32_dpp v161, v180, v180 row_ror:8 row_mask:0xf bank_mask:0xf bound_ctrl:1
	v_cndmask_b32_e64 v199, v199, v161, s[14:15]
	v_pk_fma_f32 v[196:197], v[192:193], v[160:161], v[162:163] op_sel_hi:[1,0,1]
	v_pk_fma_f32 v[34:35], v[194:195], v[160:161], v[34:35] op_sel_hi:[1,0,1]
	ds_read_b128 v[160:163], v28 offset:10752
	ds_read_b128 v[180:183], v28 offset:11008
	ds_read_b128 v[184:187], v28 offset:11264
	ds_read_b128 v[188:191], v28 offset:11776
	ds_read_b128 v[192:195], v28 offset:12032
	ds_read_b32 v200, v29 offset:11520
	s_waitcnt lgkmcnt(8)
	v_pk_mul_f32 v[174:175], v[174:175], v[34:35]
	v_pk_mul_f32 v[26:27], v[26:27], v[34:35]
	v_pk_fma_f32 v[172:173], v[172:173], v[196:197], v[174:175]
	v_pk_fma_f32 v[24:25], v[24:25], v[196:197], v[26:27]
	v_pk_mul_f32 v[26:27], v[164:165], v[196:197]
	v_add_f32_e32 v164, v172, v173
	v_add_f32_e32 v24, v24, v25
	v_pk_mul_f32 v[34:35], v[166:167], v[34:35]
	v_add_f32_dpp v25, v164, v164 quad_perm:[1,0,3,2] row_mask:0xf bank_mask:0xf bound_ctrl:1
	v_add_f32_dpp v24, v24, v24 quad_perm:[1,0,3,2] row_mask:0xf bank_mask:0xf bound_ctrl:1
	s_waitcnt lgkmcnt(6)
; #define LAS __attribute__((address_space(3)))
; __device__ __forceinline__ void rwkv_scan_prompt(const Params& p, LAS unsigned char* lds, int bh, int rq) {
;     ...
;             for (int tk = 0; tk < TC; ++tk) {
;                 f32x4 nr4 = r4, nd4 = d4, nk4 = k4, na4 = a4, nb4 = b4; float nvv = vv;
;                 if (tk < TC - 1) {
;                     const LAS float* o = ob + (tk + 1) * 6 * 64;
;                     nr4 = *(const LAS f32x4*)(o + cg_ * 4); nd4 = *(const LAS f32x4*)(o + 64 + cg_ * 4); nk4 = *(const LAS f32x4*)(o + 128 + cg_ * 4);
;                     na4 = *(const LAS f32x4*)(o + 256 + cg_ * 4); nb4 = *(const LAS f32x4*)(o + 320 + cg_ * 4);
;                     nvv = o[192 + rq * 16 + rloc];
;                 }
;                 __builtin_amdgcn_sched_barrier(0);
;                 typedef float f32x2_ __attribute__((ext_vector_type(2)));
;                 f32x2_ ta = (f32x2_){S[0], S[1]} * (f32x2_){a4[0], a4[1]}; ta = (f32x2_){S[2], S[3]} * (f32x2_){a4[2], a4[3]} + ta;
;                 f32x2_ ty = (f32x2_){S[0], S[1]} * (f32x2_){rp[0], rp[1]}; ty = (f32x2_){S[2], S[3]} * (f32x2_){rp[2], rp[3]} + ty;
;                 const f32x4 T = S * d4 + vv * k4;
;                 float sa = ta[0] + ta[1];
;                 float yp = ty[0] + ty[1];
;                 sa = dpp_add<0xB1>(sa); yp = dpp_add<0xB1>(yp);
;                 sa = dpp_add<0x4E>(sa); yp = dpp_add<0x4E>(yp);
;                 sa = dpp_add<0x124>(sa); yp = dpp_add<0x124>(yp);
;                 sa = dpp_add<0x128>(sa); yp = dpp_add<0x128>(yp);
;                 if (tk > 0) yk[(tk - 1) >> 4] = (cg_ == ((tk - 1) & 15)) ? yp : yk[(tk - 1) >> 4];
;                 S = sa * b4 + T;
;                 rp = r4;
;                 r4 = nr4; d4 = nd4; k4 = nk4; a4 = na4; b4 = nb4; vv = nvv;
;             }
	v_pk_fma_f32 v[34:35], v[170:171], v[198:199], v[34:35] op_sel_hi:[1,0,1]
	v_add_f32_dpp v25, v25, v25 quad_perm:[2,3,0,1] row_mask:0xf bank_mask:0xf bound_ctrl:1
	v_add_f32_dpp v24, v24, v24 quad_perm:[2,3,0,1] row_mask:0xf bank_mask:0xf bound_ctrl:1
	v_pk_fma_f32 v[26:27], v[168:169], v[198:199], v[26:27] op_sel_hi:[1,0,1]
	v_add_f32_dpp v25, v25, v25 row_ror:4 row_mask:0xf bank_mask:0xf bound_ctrl:1
	v_add_f32_dpp v164, v24, v24 row_ror:4 row_mask:0xf bank_mask:0xf bound_ctrl:1
	s_nop 0
	v_add_f32_dpp v24, v25, v25 row_ror:8 row_mask:0xf bank_mask:0xf bound_ctrl:1
	v_add_f32_dpp v25, v164, v164 row_ror:8 row_mask:0xf bank_mask:0xf bound_ctrl:1
	v_cndmask_b32_e64 v199, v199, v25, s[16:17]
	v_pk_fma_f32 v[196:197], v[176:177], v[24:25], v[26:27] op_sel_hi:[1,0,1]
	v_pk_fma_f32 v[34:35], v[178:179], v[24:25], v[34:35] op_sel_hi:[1,0,1]
	ds_read_b128 v[24:27], v28 offset:12288
	ds_read_b128 v[164:167], v28 offset:12544
	ds_read_b128 v[168:171], v28 offset:12800
	ds_read_b128 v[172:175], v28 offset:13312
	ds_read_b128 v[176:179], v28 offset:13568
	ds_read_b32 v198, v29 offset:13056
	s_waitcnt lgkmcnt(8)
	v_pk_mul_f32 v[190:191], v[190:191], v[34:35]
	v_pk_mul_f32 v[32:33], v[32:33], v[34:35]
	v_pk_fma_f32 v[188:189], v[188:189], v[196:197], v[190:191]
	v_pk_fma_f32 v[30:31], v[30:31], v[196:197], v[32:33]
	v_pk_mul_f32 v[32:33], v[180:181], v[196:197]
	v_add_f32_e32 v180, v188, v189
	v_add_f32_e32 v30, v30, v31
	v_pk_mul_f32 v[34:35], v[182:183], v[34:35]
	v_add_f32_dpp v31, v180, v180 quad_perm:[1,0,3,2] row_mask:0xf bank_mask:0xf bound_ctrl:1
	v_add_f32_dpp v30, v30, v30 quad_perm:[1,0,3,2] row_mask:0xf bank_mask:0xf bound_ctrl:1
	s_waitcnt lgkmcnt(6)
	v_pk_fma_f32 v[34:35], v[186:187], v[200:201], v[34:35] op_sel_hi:[1,0,1]
	v_add_f32_dpp v31, v31, v31 quad_perm:[2,3,0,1] row_mask:0xf bank_mask:0xf bound_ctrl:1
	v_add_f32_dpp v30, v30, v30 quad_perm:[2,3,0,1] row_mask:0xf bank_mask:0xf bound_ctrl:1
	v_pk_fma_f32 v[32:33], v[184:185], v[200:201], v[32:33] op_sel_hi:[1,0,1]
	v_add_f32_dpp v31, v31, v31 row_ror:4 row_mask:0xf bank_mask:0xf bound_ctrl:1
	v_add_f32_dpp v180, v30, v30 row_ror:4 row_mask:0xf bank_mask:0xf bound_ctrl:1
	s_nop 0
	v_add_f32_dpp v30, v31, v31 row_ror:8 row_mask:0xf bank_mask:0xf bound_ctrl:1
	v_add_f32_dpp v31, v180, v180 row_ror:8 row_mask:0xf bank_mask:0xf bound_ctrl:1
	v_cndmask_b32_e64 v199, v199, v31, s[18:19]
	v_pk_fma_f32 v[196:197], v[192:193], v[30:31], v[32:33] op_sel_hi:[1,0,1]
	v_pk_fma_f32 v[34:35], v[194:195], v[30:31], v[34:35] op_sel_hi:[1,0,1]
	ds_read_b128 v[30:33], v28 offset:13824
	ds_read_b128 v[180:183], v28 offset:14080
	ds_read_b128 v[184:187], v28 offset:14336
	ds_read_b128 v[188:191], v28 offset:14848
	ds_read_b128 v[192:195], v28 offset:15104
	ds_read_b32 v200, v29 offset:14592
	s_waitcnt lgkmcnt(8)
	v_pk_mul_f32 v[174:175], v[174:175], v[34:35]
	v_pk_mul_f32 v[162:163], v[162:163], v[34:35]
	v_pk_fma_f32 v[172:173], v[172:173], v[196:197], v[174:175]
	v_pk_fma_f32 v[160:161], v[160:161], v[196:197], v[162:163]
	v_pk_mul_f32 v[162:163], v[164:165], v[196:197]
	v_add_f32_e32 v164, v172, v173
	v_add_f32_e32 v160, v160, v161
	v_pk_mul_f32 v[34:35], v[166:167], v[34:35]
	v_add_f32_dpp v161, v164, v164 quad_perm:[1,0,3,2] row_mask:0xf bank_mask:0xf bound_ctrl:1
	v_add_f32_dpp v160, v160, v160 quad_perm:[1,0,3,2] row_mask:0xf bank_mask:0xf bound_ctrl:1
	s_waitcnt lgkmcnt(6)
	v_pk_fma_f32 v[34:35], v[170:171], v[198:199], v[34:35] op_sel_hi:[1,0,1]
	v_add_f32_dpp v161, v161, v161 quad_perm:[2,3,0,1] row_mask:0xf bank_mask:0xf bound_ctrl:1
	v_add_f32_dpp v160, v160, v160 quad_perm:[2,3,0,1] row_mask:0xf bank_mask:0xf bound_ctrl:1
	v_pk_fma_f32 v[162:163], v[168:169], v[198:199], v[162:163] op_sel_hi:[1,0,1]
	v_add_f32_dpp v161, v161, v161 row_ror:4 row_mask:0xf bank_mask:0xf bound_ctrl:1
	v_add_f32_dpp v164, v160, v160 row_ror:4 row_mask:0xf bank_mask:0xf bound_ctrl:1
	s_nop 0
	v_add_f32_dpp v160, v161, v161 row_ror:8 row_mask:0xf bank_mask:0xf bound_ctrl:1
	v_add_f32_dpp v161, v164, v164 row_ror:8 row_mask:0xf bank_mask:0xf bound_ctrl:1
	v_cndmask_b32_e64 v199, v199, v161, s[20:21]
	v_pk_fma_f32 v[196:197], v[176:177], v[160:161], v[162:163] op_sel_hi:[1,0,1]
	v_pk_fma_f32 v[34:35], v[178:179], v[160:161], v[34:35] op_sel_hi:[1,0,1]
	ds_read_b128 v[160:163], v28 offset:15360
	ds_read_b128 v[164:167], v28 offset:15616
	ds_read_b128 v[168:171], v28 offset:15872
	ds_read_b128 v[172:175], v28 offset:16384
	ds_read_b128 v[176:179], v28 offset:16640
	ds_read_b32 v198, v29 offset:16128
	s_waitcnt lgkmcnt(8)
	v_pk_mul_f32 v[190:191], v[190:191], v[34:35]
	v_pk_mul_f32 v[26:27], v[26:27], v[34:35]
	v_pk_fma_f32 v[188:189], v[188:189], v[196:197], v[190:191]
	v_pk_fma_f32 v[24:25], v[24:25], v[196:197], v[26:27]
	v_pk_mul_f32 v[26:27], v[180:181], v[196:197]
	v_add_f32_e32 v180, v188, v189
	v_add_f32_e32 v24, v24, v25
	v_pk_mul_f32 v[34:35], v[182:183], v[34:35]
	v_add_f32_dpp v25, v180, v180 quad_perm:[1,0,3,2] row_mask:0xf bank_mask:0xf bound_ctrl:1
	v_add_f32_dpp v24, v24, v24 quad_perm:[1,0,3,2] row_mask:0xf bank_mask:0xf bound_ctrl:1
	s_waitcnt lgkmcnt(6)
; #define LAS __attribute__((address_space(3)))
; __device__ __forceinline__ void rwkv_scan_prompt(const Params& p, LAS unsigned char* lds, int bh, int rq) {
;     ...
;             for (int tk = 0; tk < TC; ++tk) {
;                 f32x4 nr4 = r4, nd4 = d4, nk4 = k4, na4 = a4, nb4 = b4; float nvv = vv;
;                 if (tk < TC - 1) {
;                     const LAS float* o = ob + (tk + 1) * 6 * 64;
;                     nr4 = *(const LAS f32x4*)(o + cg_ * 4); nd4 = *(const LAS f32x4*)(o + 64 + cg_ * 4); nk4 = *(const LAS f32x4*)(o + 128 + cg_ * 4);
;                     na4 = *(const LAS f32x4*)(o + 256 + cg_ * 4); nb4 = *(const LAS f32x4*)(o + 320 + cg_ * 4);
;                     nvv = o[192 + rq * 16 + rloc];
;                 }
;                 __builtin_amdgcn_sched_barrier(0);
;                 typedef float f32x2_ __attribute__((ext_vector_type(2)));
;                 f32x2_ ta = (f32x2_){S[0], S[1]} * (f32x2_){a4[0], a4[1]}; ta = (f32x2_){S[2], S[3]} * (f32x2_){a4[2], a4[3]} + ta;
;                 f32x2_ ty = (f32x2_){S[0], S[1]} * (f32x2_){rp[0], rp[1]}; ty = (f32x2_){S[2], S[3]} * (f32x2_){rp[2], rp[3]} + ty;
;                 const f32x4 T = S * d4 + vv * k4;
;                 float sa = ta[0] + ta[1];
;                 float yp = ty[0] + ty[1];
;                 sa = dpp_add<0xB1>(sa); yp = dpp_add<0xB1>(yp);
;                 sa = dpp_add<0x4E>(sa); yp = dpp_add<0x4E>(yp);
;                 sa = dpp_add<0x124>(sa); yp = dpp_add<0x124>(yp);
;                 sa = dpp_add<0x128>(sa); yp = dpp_add<0x128>(yp);
;                 if (tk > 0) yk[(tk - 1) >> 4] = (cg_ == ((tk - 1) & 15)) ? yp : yk[(tk - 1) >> 4];
;                 S = sa * b4 + T;
;                 rp = r4;
;                 r4 = nr4; d4 = nd4; k4 = nk4; a4 = na4; b4 = nb4; vv = nvv;
;             }
	v_pk_fma_f32 v[34:35], v[186:187], v[200:201], v[34:35] op_sel_hi:[1,0,1]
	v_add_f32_dpp v25, v25, v25 quad_perm:[2,3,0,1] row_mask:0xf bank_mask:0xf bound_ctrl:1
	v_add_f32_dpp v24, v24, v24 quad_perm:[2,3,0,1] row_mask:0xf bank_mask:0xf bound_ctrl:1
	v_pk_fma_f32 v[26:27], v[184:185], v[200:201], v[26:27] op_sel_hi:[1,0,1]
	v_add_f32_dpp v25, v25, v25 row_ror:4 row_mask:0xf bank_mask:0xf bound_ctrl:1
	v_add_f32_dpp v180, v24, v24 row_ror:4 row_mask:0xf bank_mask:0xf bound_ctrl:1
	s_nop 0
	v_add_f32_dpp v24, v25, v25 row_ror:8 row_mask:0xf bank_mask:0xf bound_ctrl:1
	v_add_f32_dpp v25, v180, v180 row_ror:8 row_mask:0xf bank_mask:0xf bound_ctrl:1
	v_cndmask_b32_e64 v199, v199, v25, s[22:23]
	v_pk_fma_f32 v[196:197], v[192:193], v[24:25], v[26:27] op_sel_hi:[1,0,1]
	v_pk_fma_f32 v[34:35], v[194:195], v[24:25], v[34:35] op_sel_hi:[1,0,1]
	ds_read_b128 v[24:27], v28 offset:16896
	ds_read_b128 v[180:183], v28 offset:17152
	ds_read_b128 v[184:187], v28 offset:17408
	ds_read_b128 v[188:191], v28 offset:17920
	ds_read_b128 v[192:195], v28 offset:18176
	ds_read_b32 v200, v29 offset:17664
	s_waitcnt lgkmcnt(8)
	v_pk_mul_f32 v[174:175], v[174:175], v[34:35]
	v_pk_mul_f32 v[32:33], v[32:33], v[34:35]
	v_pk_fma_f32 v[172:173], v[172:173], v[196:197], v[174:175]
	v_pk_fma_f32 v[30:31], v[30:31], v[196:197], v[32:33]
	v_pk_mul_f32 v[32:33], v[164:165], v[196:197]
	v_add_f32_e32 v164, v172, v173
	v_add_f32_e32 v30, v30, v31
	v_pk_mul_f32 v[34:35], v[166:167], v[34:35]
	v_add_f32_dpp v31, v164, v164 quad_perm:[1,0,3,2] row_mask:0xf bank_mask:0xf bound_ctrl:1
	v_add_f32_dpp v30, v30, v30 quad_perm:[1,0,3,2] row_mask:0xf bank_mask:0xf bound_ctrl:1
	s_waitcnt lgkmcnt(6)
	v_pk_fma_f32 v[34:35], v[170:171], v[198:199], v[34:35] op_sel_hi:[1,0,1]
	v_add_f32_dpp v31, v31, v31 quad_perm:[2,3,0,1] row_mask:0xf bank_mask:0xf bound_ctrl:1
	v_add_f32_dpp v30, v30, v30 quad_perm:[2,3,0,1] row_mask:0xf bank_mask:0xf bound_ctrl:1
	v_pk_fma_f32 v[32:33], v[168:169], v[198:199], v[32:33] op_sel_hi:[1,0,1]
	v_add_f32_dpp v31, v31, v31 row_ror:4 row_mask:0xf bank_mask:0xf bound_ctrl:1
	v_add_f32_dpp v164, v30, v30 row_ror:4 row_mask:0xf bank_mask:0xf bound_ctrl:1
	s_nop 0
	v_add_f32_dpp v30, v31, v31 row_ror:8 row_mask:0xf bank_mask:0xf bound_ctrl:1
	v_add_f32_dpp v31, v164, v164 row_ror:8 row_mask:0xf bank_mask:0xf bound_ctrl:1
	v_cndmask_b32_e64 v199, v199, v31, s[24:25]
	v_pk_fma_f32 v[196:197], v[176:177], v[30:31], v[32:33] op_sel_hi:[1,0,1]
	v_pk_fma_f32 v[34:35], v[178:179], v[30:31], v[34:35] op_sel_hi:[1,0,1]
	ds_read_b128 v[30:33], v28 offset:18432
	ds_read_b128 v[164:167], v28 offset:18688
	ds_read_b128 v[168:171], v28 offset:18944
	ds_read_b128 v[172:175], v28 offset:19456
	ds_read_b128 v[176:179], v28 offset:19712
	ds_read_b32 v198, v29 offset:19200
	s_waitcnt lgkmcnt(8)
	v_pk_mul_f32 v[190:191], v[190:191], v[34:35]
	v_pk_mul_f32 v[162:163], v[162:163], v[34:35]
	v_pk_fma_f32 v[188:189], v[188:189], v[196:197], v[190:191]
	v_pk_fma_f32 v[160:161], v[160:161], v[196:197], v[162:163]
	v_pk_mul_f32 v[162:163], v[180:181], v[196:197]
	v_add_f32_e32 v180, v188, v189
	v_add_f32_e32 v160, v160, v161
	v_pk_mul_f32 v[34:35], v[182:183], v[34:35]
	v_add_f32_dpp v161, v180, v180 quad_perm:[1,0,3,2] row_mask:0xf bank_mask:0xf bound_ctrl:1
	v_add_f32_dpp v160, v160, v160 quad_perm:[1,0,3,2] row_mask:0xf bank_mask:0xf bound_ctrl:1
	s_waitcnt lgkmcnt(6)
	v_pk_fma_f32 v[34:35], v[186:187], v[200:201], v[34:35] op_sel_hi:[1,0,1]
	v_add_f32_dpp v161, v161, v161 quad_perm:[2,3,0,1] row_mask:0xf bank_mask:0xf bound_ctrl:1
	v_add_f32_dpp v160, v160, v160 quad_perm:[2,3,0,1] row_mask:0xf bank_mask:0xf bound_ctrl:1
	v_pk_fma_f32 v[162:163], v[184:185], v[200:201], v[162:163] op_sel_hi:[1,0,1]
	v_add_f32_dpp v161, v161, v161 row_ror:4 row_mask:0xf bank_mask:0xf bound_ctrl:1
	v_add_f32_dpp v180, v160, v160 row_ror:4 row_mask:0xf bank_mask:0xf bound_ctrl:1
	s_nop 0
	v_add_f32_dpp v160, v161, v161 row_ror:8 row_mask:0xf bank_mask:0xf bound_ctrl:1
	v_add_f32_dpp v161, v180, v180 row_ror:8 row_mask:0xf bank_mask:0xf bound_ctrl:1
	v_cndmask_b32_e64 v199, v199, v161, s[26:27]
	v_pk_fma_f32 v[196:197], v[192:193], v[160:161], v[162:163] op_sel_hi:[1,0,1]
	v_pk_fma_f32 v[34:35], v[194:195], v[160:161], v[34:35] op_sel_hi:[1,0,1]
	ds_read_b128 v[160:163], v28 offset:19968
	ds_read_b128 v[180:183], v28 offset:20224
	ds_read_b128 v[184:187], v28 offset:20480
	ds_read_b128 v[188:191], v28 offset:20992
	ds_read_b128 v[192:195], v28 offset:21248
	ds_read_b32 v200, v29 offset:20736
	s_waitcnt lgkmcnt(8)
	v_pk_mul_f32 v[174:175], v[174:175], v[34:35]
	v_pk_mul_f32 v[26:27], v[26:27], v[34:35]
	v_pk_fma_f32 v[172:173], v[172:173], v[196:197], v[174:175]
	v_pk_fma_f32 v[24:25], v[24:25], v[196:197], v[26:27]
	v_pk_mul_f32 v[26:27], v[164:165], v[196:197]
	v_add_f32_e32 v164, v172, v173
	v_add_f32_e32 v24, v24, v25
	v_pk_mul_f32 v[34:35], v[166:167], v[34:35]
	v_add_f32_dpp v25, v164, v164 quad_perm:[1,0,3,2] row_mask:0xf bank_mask:0xf bound_ctrl:1
	v_add_f32_dpp v24, v24, v24 quad_perm:[1,0,3,2] row_mask:0xf bank_mask:0xf bound_ctrl:1
	s_waitcnt lgkmcnt(6)
; #define LAS __attribute__((address_space(3)))
; __device__ __forceinline__ void rwkv_scan_prompt(const Params& p, LAS unsigned char* lds, int bh, int rq) {
;     ...
;             for (int tk = 0; tk < TC; ++tk) {
;                 f32x4 nr4 = r4, nd4 = d4, nk4 = k4, na4 = a4, nb4 = b4; float nvv = vv;
;                 if (tk < TC - 1) {
;                     const LAS float* o = ob + (tk + 1) * 6 * 64;
;                     nr4 = *(const LAS f32x4*)(o + cg_ * 4); nd4 = *(const LAS f32x4*)(o + 64 + cg_ * 4); nk4 = *(const LAS f32x4*)(o + 128 + cg_ * 4);
;                     na4 = *(const LAS f32x4*)(o + 256 + cg_ * 4); nb4 = *(const LAS f32x4*)(o + 320 + cg_ * 4);
;                     nvv = o[192 + rq * 16 + rloc];
;                 }
;                 __builtin_amdgcn_sched_barrier(0);
;                 typedef float f32x2_ __attribute__((ext_vector_type(2)));
;                 f32x2_ ta = (f32x2_){S[0], S[1]} * (f32x2_){a4[0], a4[1]}; ta = (f32x2_){S[2], S[3]} * (f32x2_){a4[2], a4[3]} + ta;
;                 f32x2_ ty = (f32x2_){S[0], S[1]} * (f32x2_){rp[0], rp[1]}; ty = (f32x2_){S[2], S[3]} * (f32x2_){rp[2], rp[3]} + ty;
;                 const f32x4 T = S * d4 + vv * k4;
;                 float sa = ta[0] + ta[1];
;                 float yp = ty[0] + ty[1];
;                 sa = dpp_add<0xB1>(sa); yp = dpp_add<0xB1>(yp);
;                 sa = dpp_add<0x4E>(sa); yp = dpp_add<0x4E>(yp);
;                 sa = dpp_add<0x124>(sa); yp = dpp_add<0x124>(yp);
;                 sa = dpp_add<0x128>(sa); yp = dpp_add<0x128>(yp);
;                 if (tk > 0) yk[(tk - 1) >> 4] = (cg_ == ((tk - 1) & 15)) ? yp : yk[(tk - 1) >> 4];
;                 S = sa * b4 + T;
;                 rp = r4;
;                 r4 = nr4; d4 = nd4; k4 = nk4; a4 = na4; b4 = nb4; vv = nvv;
;             }
	v_pk_fma_f32 v[34:35], v[170:171], v[198:199], v[34:35] op_sel_hi:[1,0,1]
	v_add_f32_dpp v25, v25, v25 quad_perm:[2,3,0,1] row_mask:0xf bank_mask:0xf bound_ctrl:1
	v_add_f32_dpp v24, v24, v24 quad_perm:[2,3,0,1] row_mask:0xf bank_mask:0xf bound_ctrl:1
	v_pk_fma_f32 v[26:27], v[168:169], v[198:199], v[26:27] op_sel_hi:[1,0,1]
	v_add_f32_dpp v25, v25, v25 row_ror:4 row_mask:0xf bank_mask:0xf bound_ctrl:1
	v_add_f32_dpp v164, v24, v24 row_ror:4 row_mask:0xf bank_mask:0xf bound_ctrl:1
	s_nop 0
	v_add_f32_dpp v24, v25, v25 row_ror:8 row_mask:0xf bank_mask:0xf bound_ctrl:1
	v_add_f32_dpp v25, v164, v164 row_ror:8 row_mask:0xf bank_mask:0xf bound_ctrl:1
	v_cndmask_b32_e64 v199, v199, v25, s[28:29]
	v_pk_fma_f32 v[196:197], v[176:177], v[24:25], v[26:27] op_sel_hi:[1,0,1]
	v_pk_fma_f32 v[34:35], v[178:179], v[24:25], v[34:35] op_sel_hi:[1,0,1]
	ds_read_b128 v[24:27], v28 offset:21504
	ds_read_b128 v[164:167], v28 offset:21760
	ds_read_b128 v[168:171], v28 offset:22016
	ds_read_b128 v[172:175], v28 offset:22528
	ds_read_b128 v[176:179], v28 offset:22784
	ds_read_b32 v198, v29 offset:22272
	s_waitcnt lgkmcnt(8)
	v_pk_mul_f32 v[190:191], v[190:191], v[34:35]
	v_pk_mul_f32 v[32:33], v[32:33], v[34:35]
	v_pk_fma_f32 v[188:189], v[188:189], v[196:197], v[190:191]
	v_pk_fma_f32 v[30:31], v[30:31], v[196:197], v[32:33]
	v_pk_mul_f32 v[32:33], v[180:181], v[196:197]
	v_add_f32_e32 v180, v188, v189
	v_add_f32_e32 v30, v30, v31
	v_pk_mul_f32 v[34:35], v[182:183], v[34:35]
	v_add_f32_dpp v31, v180, v180 quad_perm:[1,0,3,2] row_mask:0xf bank_mask:0xf bound_ctrl:1
	v_add_f32_dpp v30, v30, v30 quad_perm:[1,0,3,2] row_mask:0xf bank_mask:0xf bound_ctrl:1
	s_waitcnt lgkmcnt(6)
	v_pk_fma_f32 v[34:35], v[186:187], v[200:201], v[34:35] op_sel_hi:[1,0,1]
	v_add_f32_dpp v31, v31, v31 quad_perm:[2,3,0,1] row_mask:0xf bank_mask:0xf bound_ctrl:1
	v_add_f32_dpp v30, v30, v30 quad_perm:[2,3,0,1] row_mask:0xf bank_mask:0xf bound_ctrl:1
	v_pk_fma_f32 v[32:33], v[184:185], v[200:201], v[32:33] op_sel_hi:[1,0,1]
	v_add_f32_dpp v31, v31, v31 row_ror:4 row_mask:0xf bank_mask:0xf bound_ctrl:1
	v_add_f32_dpp v180, v30, v30 row_ror:4 row_mask:0xf bank_mask:0xf bound_ctrl:1
	s_nop 0
	v_add_f32_dpp v30, v31, v31 row_ror:8 row_mask:0xf bank_mask:0xf bound_ctrl:1
	v_add_f32_dpp v31, v180, v180 row_ror:8 row_mask:0xf bank_mask:0xf bound_ctrl:1
	v_cndmask_b32_e64 v199, v199, v31, s[30:31]
	v_pk_fma_f32 v[196:197], v[192:193], v[30:31], v[32:33] op_sel_hi:[1,0,1]
	v_pk_fma_f32 v[34:35], v[194:195], v[30:31], v[34:35] op_sel_hi:[1,0,1]
	ds_read_b128 v[30:33], v28 offset:23040
	ds_read_b128 v[180:183], v28 offset:23296
	ds_read_b128 v[184:187], v28 offset:23552
	ds_read_b128 v[188:191], v28 offset:24064
	ds_read_b128 v[192:195], v28 offset:24320
	ds_read_b32 v200, v29 offset:23808
	s_waitcnt lgkmcnt(8)
	v_pk_mul_f32 v[174:175], v[174:175], v[34:35]
	v_pk_mul_f32 v[162:163], v[162:163], v[34:35]
	v_pk_fma_f32 v[172:173], v[172:173], v[196:197], v[174:175]
	v_pk_fma_f32 v[160:161], v[160:161], v[196:197], v[162:163]
	v_pk_mul_f32 v[162:163], v[164:165], v[196:197]
	v_add_f32_e32 v164, v172, v173
	v_add_f32_e32 v160, v160, v161
	v_pk_mul_f32 v[34:35], v[166:167], v[34:35]
	v_add_f32_dpp v161, v164, v164 quad_perm:[1,0,3,2] row_mask:0xf bank_mask:0xf bound_ctrl:1
	v_add_f32_dpp v160, v160, v160 quad_perm:[1,0,3,2] row_mask:0xf bank_mask:0xf bound_ctrl:1
	s_waitcnt lgkmcnt(6)
	v_pk_fma_f32 v[34:35], v[170:171], v[198:199], v[34:35] op_sel_hi:[1,0,1]
	v_add_f32_dpp v161, v161, v161 quad_perm:[2,3,0,1] row_mask:0xf bank_mask:0xf bound_ctrl:1
	v_add_f32_dpp v160, v160, v160 quad_perm:[2,3,0,1] row_mask:0xf bank_mask:0xf bound_ctrl:1
	v_pk_fma_f32 v[162:163], v[168:169], v[198:199], v[162:163] op_sel_hi:[1,0,1]
	v_add_f32_dpp v161, v161, v161 row_ror:4 row_mask:0xf bank_mask:0xf bound_ctrl:1
	v_add_f32_dpp v164, v160, v160 row_ror:4 row_mask:0xf bank_mask:0xf bound_ctrl:1
	s_nop 0
	v_add_f32_dpp v160, v161, v161 row_ror:8 row_mask:0xf bank_mask:0xf bound_ctrl:1
	v_add_f32_dpp v161, v164, v164 row_ror:8 row_mask:0xf bank_mask:0xf bound_ctrl:1
	v_cndmask_b32_e64 v199, v199, v161, s[34:35]
	v_pk_fma_f32 v[196:197], v[176:177], v[160:161], v[162:163] op_sel_hi:[1,0,1]
	v_pk_fma_f32 v[34:35], v[178:179], v[160:161], v[34:35] op_sel_hi:[1,0,1]
	ds_read_b128 v[160:163], v28 offset:24576
	ds_read_b128 v[164:167], v28 offset:24832
	ds_read_b128 v[168:171], v28 offset:25088
	ds_read_b128 v[172:175], v28 offset:25600
	ds_read_b128 v[176:179], v28 offset:25856
	ds_read_b32 v198, v29 offset:25344
	s_waitcnt lgkmcnt(8)
	v_pk_mul_f32 v[190:191], v[190:191], v[34:35]
	v_pk_mul_f32 v[26:27], v[26:27], v[34:35]
	v_pk_fma_f32 v[188:189], v[188:189], v[196:197], v[190:191]
	v_pk_fma_f32 v[24:25], v[24:25], v[196:197], v[26:27]
	v_pk_mul_f32 v[26:27], v[180:181], v[196:197]
	v_add_f32_e32 v180, v188, v189
	v_add_f32_e32 v24, v24, v25
	v_pk_mul_f32 v[34:35], v[182:183], v[34:35]
	v_add_f32_dpp v25, v180, v180 quad_perm:[1,0,3,2] row_mask:0xf bank_mask:0xf bound_ctrl:1
	v_add_f32_dpp v24, v24, v24 quad_perm:[1,0,3,2] row_mask:0xf bank_mask:0xf bound_ctrl:1
	s_waitcnt lgkmcnt(6)
; #define LAS __attribute__((address_space(3)))
; __device__ __forceinline__ void rwkv_scan_prompt(const Params& p, LAS unsigned char* lds, int bh, int rq) {
;     ...
;             for (int tk = 0; tk < TC; ++tk) {
;                 f32x4 nr4 = r4, nd4 = d4, nk4 = k4, na4 = a4, nb4 = b4; float nvv = vv;
;                 if (tk < TC - 1) {
;                     const LAS float* o = ob + (tk + 1) * 6 * 64;
;                     nr4 = *(const LAS f32x4*)(o + cg_ * 4); nd4 = *(const LAS f32x4*)(o + 64 + cg_ * 4); nk4 = *(const LAS f32x4*)(o + 128 + cg_ * 4);
;                     na4 = *(const LAS f32x4*)(o + 256 + cg_ * 4); nb4 = *(const LAS f32x4*)(o + 320 + cg_ * 4);
;                     nvv = o[192 + rq * 16 + rloc];
;                 }
;                 __builtin_amdgcn_sched_barrier(0);
;                 typedef float f32x2_ __attribute__((ext_vector_type(2)));
;                 f32x2_ ta = (f32x2_){S[0], S[1]} * (f32x2_){a4[0], a4[1]}; ta = (f32x2_){S[2], S[3]} * (f32x2_){a4[2], a4[3]} + ta;
;                 f32x2_ ty = (f32x2_){S[0], S[1]} * (f32x2_){rp[0], rp[1]}; ty = (f32x2_){S[2], S[3]} * (f32x2_){rp[2], rp[3]} + ty;
;                 const f32x4 T = S * d4 + vv * k4;
;                 float sa = ta[0] + ta[1];
;                 float yp = ty[0] + ty[1];
;                 sa = dpp_add<0xB1>(sa); yp = dpp_add<0xB1>(yp);
;                 sa = dpp_add<0x4E>(sa); yp = dpp_add<0x4E>(yp);
;                 sa = dpp_add<0x124>(sa); yp = dpp_add<0x124>(yp);
;                 sa = dpp_add<0x128>(sa); yp = dpp_add<0x128>(yp);
;                 if (tk > 0) yk[(tk - 1) >> 4] = (cg_ == ((tk - 1) & 15)) ? yp : yk[(tk - 1) >> 4];
;                 S = sa * b4 + T;
;                 rp = r4;
;                 r4 = nr4; d4 = nd4; k4 = nk4; a4 = na4; b4 = nb4; vv = nvv;
;             }
	v_pk_fma_f32 v[34:35], v[186:187], v[200:201], v[34:35] op_sel_hi:[1,0,1]
	v_add_f32_dpp v25, v25, v25 quad_perm:[2,3,0,1] row_mask:0xf bank_mask:0xf bound_ctrl:1
	v_add_f32_dpp v24, v24, v24 quad_perm:[2,3,0,1] row_mask:0xf bank_mask:0xf bound_ctrl:1
	v_pk_fma_f32 v[26:27], v[184:185], v[200:201], v[26:27] op_sel_hi:[1,0,1]
	v_add_f32_dpp v25, v25, v25 row_ror:4 row_mask:0xf bank_mask:0xf bound_ctrl:1
	v_add_f32_dpp v180, v24, v24 row_ror:4 row_mask:0xf bank_mask:0xf bound_ctrl:1
	s_nop 0
	v_add_f32_dpp v24, v25, v25 row_ror:8 row_mask:0xf bank_mask:0xf bound_ctrl:1
	v_add_f32_dpp v25, v180, v180 row_ror:8 row_mask:0xf bank_mask:0xf bound_ctrl:1
	v_cndmask_b32_e64 v199, v199, v25, s[36:37]
	v_pk_fma_f32 v[196:197], v[192:193], v[24:25], v[26:27] op_sel_hi:[1,0,1]
	v_pk_fma_f32 v[34:35], v[194:195], v[24:25], v[34:35] op_sel_hi:[1,0,1]
	ds_read_b128 v[24:27], v28 offset:26112
	ds_read_b128 v[180:183], v28 offset:26368
	ds_read_b128 v[184:187], v28 offset:26624
	ds_read_b128 v[188:191], v28 offset:27136
	ds_read_b128 v[192:195], v28 offset:27392
	ds_read_b32 v200, v29 offset:26880
	s_waitcnt lgkmcnt(8)
	v_pk_mul_f32 v[174:175], v[174:175], v[34:35]
	v_pk_mul_f32 v[32:33], v[32:33], v[34:35]
	v_pk_fma_f32 v[172:173], v[172:173], v[196:197], v[174:175]
	v_pk_fma_f32 v[30:31], v[30:31], v[196:197], v[32:33]
	v_pk_mul_f32 v[32:33], v[164:165], v[196:197]
	v_add_f32_e32 v164, v172, v173
	v_add_f32_e32 v30, v30, v31
	v_pk_mul_f32 v[34:35], v[166:167], v[34:35]
	v_add_f32_dpp v31, v164, v164 quad_perm:[1,0,3,2] row_mask:0xf bank_mask:0xf bound_ctrl:1
	v_add_f32_dpp v30, v30, v30 quad_perm:[1,0,3,2] row_mask:0xf bank_mask:0xf bound_ctrl:1
	s_waitcnt lgkmcnt(6)
	v_pk_fma_f32 v[34:35], v[170:171], v[198:199], v[34:35] op_sel_hi:[1,0,1]
	v_add_f32_dpp v31, v31, v31 quad_perm:[2,3,0,1] row_mask:0xf bank_mask:0xf bound_ctrl:1
	v_add_f32_dpp v30, v30, v30 quad_perm:[2,3,0,1] row_mask:0xf bank_mask:0xf bound_ctrl:1
	v_pk_fma_f32 v[32:33], v[168:169], v[198:199], v[32:33] op_sel_hi:[1,0,1]
	v_add_f32_dpp v31, v31, v31 row_ror:4 row_mask:0xf bank_mask:0xf bound_ctrl:1
	v_add_f32_dpp v30, v30, v30 row_ror:4 row_mask:0xf bank_mask:0xf bound_ctrl:1
	s_nop 0
	v_add_f32_dpp v164, v31, v31 row_ror:8 row_mask:0xf bank_mask:0xf bound_ctrl:1
	v_add_f32_dpp v30, v30, v30 row_ror:8 row_mask:0xf bank_mask:0xf bound_ctrl:1
	v_cndmask_b32_e64 v30, v199, v30, s[4:5]
	v_pk_fma_f32 v[196:197], v[176:177], v[164:165], v[32:33] op_sel_hi:[1,0,1]
	v_pk_fma_f32 v[198:199], v[178:179], v[164:165], v[34:35] op_sel_hi:[1,0,1]
	ds_read_b128 v[32:35], v28 offset:27648
	ds_read_b128 v[164:167], v28 offset:27904
	ds_read_b128 v[168:171], v28 offset:28160
	ds_read_b128 v[172:175], v28 offset:28672
	ds_read_b128 v[176:179], v28 offset:28928
	ds_read_b32 v202, v29 offset:28416
	s_waitcnt lgkmcnt(8)
	v_pk_mul_f32 v[190:191], v[190:191], v[198:199]
	v_pk_mul_f32 v[162:163], v[162:163], v[198:199]
	v_pk_fma_f32 v[188:189], v[188:189], v[196:197], v[190:191]
	v_pk_fma_f32 v[160:161], v[160:161], v[196:197], v[162:163]
	v_add_f32_e32 v31, v188, v189
	v_add_f32_e32 v160, v160, v161
	v_pk_mul_f32 v[162:163], v[180:181], v[196:197]
	v_add_f32_dpp v31, v31, v31 quad_perm:[1,0,3,2] row_mask:0xf bank_mask:0xf bound_ctrl:1
	v_add_f32_dpp v160, v160, v160 quad_perm:[1,0,3,2] row_mask:0xf bank_mask:0xf bound_ctrl:1
	v_pk_mul_f32 v[180:181], v[182:183], v[198:199]
	v_add_f32_dpp v31, v31, v31 quad_perm:[2,3,0,1] row_mask:0xf bank_mask:0xf bound_ctrl:1
	v_add_f32_dpp v160, v160, v160 quad_perm:[2,3,0,1] row_mask:0xf bank_mask:0xf bound_ctrl:1
	s_waitcnt lgkmcnt(6)
	v_pk_fma_f32 v[180:181], v[186:187], v[200:201], v[180:181] op_sel_hi:[1,0,1]
	v_add_f32_dpp v31, v31, v31 row_ror:4 row_mask:0xf bank_mask:0xf bound_ctrl:1
	v_pk_fma_f32 v[162:163], v[184:185], v[200:201], v[162:163] op_sel_hi:[1,0,1]
	v_add_f32_dpp v161, v160, v160 row_ror:4 row_mask:0xf bank_mask:0xf bound_ctrl:1
	v_add_f32_dpp v160, v31, v31 row_ror:8 row_mask:0xf bank_mask:0xf bound_ctrl:1
	v_pk_fma_f32 v[196:197], v[192:193], v[160:161], v[162:163] op_sel_hi:[1,0,1]
	v_add_f32_dpp v31, v161, v161 row_ror:8 row_mask:0xf bank_mask:0xf bound_ctrl:1
	v_pk_fma_f32 v[198:199], v[194:195], v[160:161], v[180:181] op_sel_hi:[1,0,1]
	ds_read_b128 v[160:163], v28 offset:29184
	ds_read_b128 v[180:183], v28 offset:29440
	ds_read_b128 v[184:187], v28 offset:29696
	ds_read_b128 v[188:191], v28 offset:30208
	ds_read_b128 v[192:195], v28 offset:30464
	ds_read_b32 v200, v29 offset:29952
	v_cndmask_b32_e64 v31, 0, v31, s[6:7]
	s_waitcnt lgkmcnt(8)
	v_pk_mul_f32 v[174:175], v[174:175], v[198:199]
	v_pk_mul_f32 v[26:27], v[26:27], v[198:199]
	v_pk_fma_f32 v[172:173], v[172:173], v[196:197], v[174:175]
	v_pk_fma_f32 v[24:25], v[24:25], v[196:197], v[26:27]
	v_pk_mul_f32 v[26:27], v[164:165], v[196:197]
	v_pk_mul_f32 v[164:165], v[166:167], v[198:199]
	v_add_f32_e32 v166, v172, v173
	v_add_f32_e32 v24, v24, v25
	s_waitcnt lgkmcnt(6)
	v_pk_fma_f32 v[164:165], v[170:171], v[202:203], v[164:165] op_sel_hi:[1,0,1]
	v_add_f32_dpp v25, v166, v166 quad_perm:[1,0,3,2] row_mask:0xf bank_mask:0xf bound_ctrl:1
	v_add_f32_dpp v24, v24, v24 quad_perm:[1,0,3,2] row_mask:0xf bank_mask:0xf bound_ctrl:1
	v_pk_fma_f32 v[26:27], v[168:169], v[202:203], v[26:27] op_sel_hi:[1,0,1]
	v_add_f32_dpp v25, v25, v25 quad_perm:[2,3,0,1] row_mask:0xf bank_mask:0xf bound_ctrl:1
	v_add_f32_dpp v24, v24, v24 quad_perm:[2,3,0,1] row_mask:0xf bank_mask:0xf bound_ctrl:1
	s_nop 0
	v_add_f32_dpp v25, v25, v25 row_ror:4 row_mask:0xf bank_mask:0xf bound_ctrl:1
	v_add_f32_dpp v166, v24, v24 row_ror:4 row_mask:0xf bank_mask:0xf bound_ctrl:1
	s_nop 0
	v_add_f32_dpp v24, v25, v25 row_ror:8 row_mask:0xf bank_mask:0xf bound_ctrl:1
	v_add_f32_dpp v25, v166, v166 row_ror:8 row_mask:0xf bank_mask:0xf bound_ctrl:1
	v_cndmask_b32_e64 v31, v31, v25, s[8:9]
	v_pk_fma_f32 v[196:197], v[176:177], v[24:25], v[26:27] op_sel_hi:[1,0,1]
	v_pk_fma_f32 v[198:199], v[178:179], v[24:25], v[164:165] op_sel_hi:[1,0,1]
	ds_read_b128 v[24:27], v28 offset:30720
	ds_read_b128 v[164:167], v28 offset:30976
	ds_read_b128 v[168:171], v28 offset:31232
	ds_read_b128 v[172:175], v28 offset:31744
	ds_read_b128 v[176:179], v28 offset:32000
	ds_read_b32 v202, v29 offset:31488
	s_waitcnt lgkmcnt(8)
; #define LAS __attribute__((address_space(3)))
; __device__ __forceinline__ void rwkv_scan_prompt(const Params& p, LAS unsigned char* lds, int bh, int rq) {
;     ...
;             for (int tk = 0; tk < TC; ++tk) {
;                 f32x4 nr4 = r4, nd4 = d4, nk4 = k4, na4 = a4, nb4 = b4; float nvv = vv;
;                 if (tk < TC - 1) {
;                     const LAS float* o = ob + (tk + 1) * 6 * 64;
;                     nr4 = *(const LAS f32x4*)(o + cg_ * 4); nd4 = *(const LAS f32x4*)(o + 64 + cg_ * 4); nk4 = *(const LAS f32x4*)(o + 128 + cg_ * 4);
;                     na4 = *(const LAS f32x4*)(o + 256 + cg_ * 4); nb4 = *(const LAS f32x4*)(o + 320 + cg_ * 4);
;                     nvv = o[192 + rq * 16 + rloc];
;                 }
;                 __builtin_amdgcn_sched_barrier(0);
;                 typedef float f32x2_ __attribute__((ext_vector_type(2)));
;                 f32x2_ ta = (f32x2_){S[0], S[1]} * (f32x2_){a4[0], a4[1]}; ta = (f32x2_){S[2], S[3]} * (f32x2_){a4[2], a4[3]} + ta;
;                 f32x2_ ty = (f32x2_){S[0], S[1]} * (f32x2_){rp[0], rp[1]}; ty = (f32x2_){S[2], S[3]} * (f32x2_){rp[2], rp[3]} + ty;
;                 const f32x4 T = S * d4 + vv * k4;
;                 float sa = ta[0] + ta[1];
;                 float yp = ty[0] + ty[1];
;                 sa = dpp_add<0xB1>(sa); yp = dpp_add<0xB1>(yp);
;                 sa = dpp_add<0x4E>(sa); yp = dpp_add<0x4E>(yp);
;                 sa = dpp_add<0x124>(sa); yp = dpp_add<0x124>(yp);
;                 sa = dpp_add<0x128>(sa); yp = dpp_add<0x128>(yp);
;                 if (tk > 0) yk[(tk - 1) >> 4] = (cg_ == ((tk - 1) & 15)) ? yp : yk[(tk - 1) >> 4];
;                 S = sa * b4 + T;
;                 rp = r4;
;                 r4 = nr4; d4 = nd4; k4 = nk4; a4 = na4; b4 = nb4; vv = nvv;
;             }
	v_pk_mul_f32 v[190:191], v[190:191], v[198:199]
	v_pk_mul_f32 v[34:35], v[34:35], v[198:199]
	v_pk_fma_f32 v[188:189], v[188:189], v[196:197], v[190:191]
	v_pk_fma_f32 v[32:33], v[32:33], v[196:197], v[34:35]
	v_pk_mul_f32 v[34:35], v[180:181], v[196:197]
	v_pk_mul_f32 v[180:181], v[182:183], v[198:199]
	v_add_f32_e32 v182, v188, v189
	v_add_f32_e32 v32, v32, v33
	s_waitcnt lgkmcnt(6)
	v_pk_fma_f32 v[180:181], v[186:187], v[200:201], v[180:181] op_sel_hi:[1,0,1]
	v_add_f32_dpp v33, v182, v182 quad_perm:[1,0,3,2] row_mask:0xf bank_mask:0xf bound_ctrl:1
	v_add_f32_dpp v32, v32, v32 quad_perm:[1,0,3,2] row_mask:0xf bank_mask:0xf bound_ctrl:1
	v_pk_fma_f32 v[34:35], v[184:185], v[200:201], v[34:35] op_sel_hi:[1,0,1]
	v_add_f32_dpp v33, v33, v33 quad_perm:[2,3,0,1] row_mask:0xf bank_mask:0xf bound_ctrl:1
	v_add_f32_dpp v32, v32, v32 quad_perm:[2,3,0,1] row_mask:0xf bank_mask:0xf bound_ctrl:1
	s_nop 0
	v_add_f32_dpp v33, v33, v33 row_ror:4 row_mask:0xf bank_mask:0xf bound_ctrl:1
	v_add_f32_dpp v182, v32, v32 row_ror:4 row_mask:0xf bank_mask:0xf bound_ctrl:1
	s_nop 0
	v_add_f32_dpp v32, v33, v33 row_ror:8 row_mask:0xf bank_mask:0xf bound_ctrl:1
	v_add_f32_dpp v33, v182, v182 row_ror:8 row_mask:0xf bank_mask:0xf bound_ctrl:1
	v_cndmask_b32_e64 v31, v31, v33, s[10:11]
	v_pk_fma_f32 v[196:197], v[192:193], v[32:33], v[34:35] op_sel_hi:[1,0,1]
	v_pk_fma_f32 v[198:199], v[194:195], v[32:33], v[180:181] op_sel_hi:[1,0,1]
	ds_read_b128 v[32:35], v28 offset:32256
	ds_read_b128 v[180:183], v28 offset:32512
	ds_read_b128 v[184:187], v28 offset:32768
	ds_read_b128 v[188:191], v28 offset:33280
	ds_read_b128 v[192:195], v28 offset:33536
	ds_read_b32 v200, v29 offset:33024
	s_waitcnt lgkmcnt(8)
	v_pk_mul_f32 v[174:175], v[174:175], v[198:199]
	v_pk_mul_f32 v[162:163], v[162:163], v[198:199]
	v_pk_fma_f32 v[172:173], v[172:173], v[196:197], v[174:175]
	v_pk_fma_f32 v[160:161], v[160:161], v[196:197], v[162:163]
	v_pk_mul_f32 v[162:163], v[164:165], v[196:197]
	v_pk_mul_f32 v[164:165], v[166:167], v[198:199]
	v_add_f32_e32 v166, v172, v173
	v_add_f32_e32 v160, v160, v161
	s_waitcnt lgkmcnt(6)
	v_pk_fma_f32 v[164:165], v[170:171], v[202:203], v[164:165] op_sel_hi:[1,0,1]
	v_add_f32_dpp v161, v166, v166 quad_perm:[1,0,3,2] row_mask:0xf bank_mask:0xf bound_ctrl:1
	v_add_f32_dpp v160, v160, v160 quad_perm:[1,0,3,2] row_mask:0xf bank_mask:0xf bound_ctrl:1
	v_pk_fma_f32 v[162:163], v[168:169], v[202:203], v[162:163] op_sel_hi:[1,0,1]
	v_add_f32_dpp v161, v161, v161 quad_perm:[2,3,0,1] row_mask:0xf bank_mask:0xf bound_ctrl:1
	v_add_f32_dpp v160, v160, v160 quad_perm:[2,3,0,1] row_mask:0xf bank_mask:0xf bound_ctrl:1
	s_nop 0
	v_add_f32_dpp v161, v161, v161 row_ror:4 row_mask:0xf bank_mask:0xf bound_ctrl:1
	v_add_f32_dpp v166, v160, v160 row_ror:4 row_mask:0xf bank_mask:0xf bound_ctrl:1
	s_nop 0
	v_add_f32_dpp v160, v161, v161 row_ror:8 row_mask:0xf bank_mask:0xf bound_ctrl:1
	v_add_f32_dpp v161, v166, v166 row_ror:8 row_mask:0xf bank_mask:0xf bound_ctrl:1
	v_cndmask_b32_e64 v31, v31, v161, s[12:13]
	v_pk_fma_f32 v[196:197], v[176:177], v[160:161], v[162:163] op_sel_hi:[1,0,1]
	v_pk_fma_f32 v[198:199], v[178:179], v[160:161], v[164:165] op_sel_hi:[1,0,1]
	ds_read_b128 v[160:163], v28 offset:33792
	ds_read_b128 v[164:167], v28 offset:34048
	ds_read_b128 v[168:171], v28 offset:34304
	ds_read_b128 v[172:175], v28 offset:34816
	ds_read_b128 v[176:179], v28 offset:35072
	ds_read_b32 v202, v29 offset:34560
	s_waitcnt lgkmcnt(8)
	v_pk_mul_f32 v[190:191], v[190:191], v[198:199]
	v_pk_mul_f32 v[26:27], v[26:27], v[198:199]
	v_pk_fma_f32 v[188:189], v[188:189], v[196:197], v[190:191]
	v_pk_fma_f32 v[24:25], v[24:25], v[196:197], v[26:27]
	v_pk_mul_f32 v[26:27], v[180:181], v[196:197]
	v_pk_mul_f32 v[180:181], v[182:183], v[198:199]
	v_add_f32_e32 v182, v188, v189
	v_add_f32_e32 v24, v24, v25
	s_waitcnt lgkmcnt(6)
	v_pk_fma_f32 v[180:181], v[186:187], v[200:201], v[180:181] op_sel_hi:[1,0,1]
	v_add_f32_dpp v25, v182, v182 quad_perm:[1,0,3,2] row_mask:0xf bank_mask:0xf bound_ctrl:1
	v_add_f32_dpp v24, v24, v24 quad_perm:[1,0,3,2] row_mask:0xf bank_mask:0xf bound_ctrl:1
	v_pk_fma_f32 v[26:27], v[184:185], v[200:201], v[26:27] op_sel_hi:[1,0,1]
	v_add_f32_dpp v25, v25, v25 quad_perm:[2,3,0,1] row_mask:0xf bank_mask:0xf bound_ctrl:1
	v_add_f32_dpp v24, v24, v24 quad_perm:[2,3,0,1] row_mask:0xf bank_mask:0xf bound_ctrl:1
	s_nop 0
	v_add_f32_dpp v25, v25, v25 row_ror:4 row_mask:0xf bank_mask:0xf bound_ctrl:1
	v_add_f32_dpp v182, v24, v24 row_ror:4 row_mask:0xf bank_mask:0xf bound_ctrl:1
	s_nop 0
	v_add_f32_dpp v24, v25, v25 row_ror:8 row_mask:0xf bank_mask:0xf bound_ctrl:1
	v_add_f32_dpp v25, v182, v182 row_ror:8 row_mask:0xf bank_mask:0xf bound_ctrl:1
	v_cndmask_b32_e64 v31, v31, v25, s[14:15]
	v_pk_fma_f32 v[196:197], v[192:193], v[24:25], v[26:27] op_sel_hi:[1,0,1]
	v_pk_fma_f32 v[198:199], v[194:195], v[24:25], v[180:181] op_sel_hi:[1,0,1]
	ds_read_b128 v[24:27], v28 offset:35328
	ds_read_b128 v[180:183], v28 offset:35584
	ds_read_b128 v[184:187], v28 offset:35840
	ds_read_b128 v[188:191], v28 offset:36352
	ds_read_b128 v[192:195], v28 offset:36608
	ds_read_b32 v200, v29 offset:36096
	s_waitcnt lgkmcnt(8)
	v_pk_mul_f32 v[174:175], v[174:175], v[198:199]
	v_pk_mul_f32 v[34:35], v[34:35], v[198:199]
	v_pk_fma_f32 v[172:173], v[172:173], v[196:197], v[174:175]
	v_pk_fma_f32 v[32:33], v[32:33], v[196:197], v[34:35]
	v_pk_mul_f32 v[34:35], v[164:165], v[196:197]
	v_pk_mul_f32 v[164:165], v[166:167], v[198:199]
	v_add_f32_e32 v166, v172, v173
	v_add_f32_e32 v32, v32, v33
	s_waitcnt lgkmcnt(6)
; #define LAS __attribute__((address_space(3)))
; __device__ __forceinline__ void rwkv_scan_prompt(const Params& p, LAS unsigned char* lds, int bh, int rq) {
;     ...
;             for (int tk = 0; tk < TC; ++tk) {
;                 f32x4 nr4 = r4, nd4 = d4, nk4 = k4, na4 = a4, nb4 = b4; float nvv = vv;
;                 if (tk < TC - 1) {
;                     const LAS float* o = ob + (tk + 1) * 6 * 64;
;                     nr4 = *(const LAS f32x4*)(o + cg_ * 4); nd4 = *(const LAS f32x4*)(o + 64 + cg_ * 4); nk4 = *(const LAS f32x4*)(o + 128 + cg_ * 4);
;                     na4 = *(const LAS f32x4*)(o + 256 + cg_ * 4); nb4 = *(const LAS f32x4*)(o + 320 + cg_ * 4);
;                     nvv = o[192 + rq * 16 + rloc];
;                 }
;                 __builtin_amdgcn_sched_barrier(0);
;                 typedef float f32x2_ __attribute__((ext_vector_type(2)));
;                 f32x2_ ta = (f32x2_){S[0], S[1]} * (f32x2_){a4[0], a4[1]}; ta = (f32x2_){S[2], S[3]} * (f32x2_){a4[2], a4[3]} + ta;
;                 f32x2_ ty = (f32x2_){S[0], S[1]} * (f32x2_){rp[0], rp[1]}; ty = (f32x2_){S[2], S[3]} * (f32x2_){rp[2], rp[3]} + ty;
;                 const f32x4 T = S * d4 + vv * k4;
;                 float sa = ta[0] + ta[1];
;                 float yp = ty[0] + ty[1];
;                 sa = dpp_add<0xB1>(sa); yp = dpp_add<0xB1>(yp);
;                 sa = dpp_add<0x4E>(sa); yp = dpp_add<0x4E>(yp);
;                 sa = dpp_add<0x124>(sa); yp = dpp_add<0x124>(yp);
;                 sa = dpp_add<0x128>(sa); yp = dpp_add<0x128>(yp);
;                 if (tk > 0) yk[(tk - 1) >> 4] = (cg_ == ((tk - 1) & 15)) ? yp : yk[(tk - 1) >> 4];
;                 S = sa * b4 + T;
;                 rp = r4;
;                 r4 = nr4; d4 = nd4; k4 = nk4; a4 = na4; b4 = nb4; vv = nvv;
;             }
	v_pk_fma_f32 v[164:165], v[170:171], v[202:203], v[164:165] op_sel_hi:[1,0,1]
	v_add_f32_dpp v33, v166, v166 quad_perm:[1,0,3,2] row_mask:0xf bank_mask:0xf bound_ctrl:1
	v_add_f32_dpp v32, v32, v32 quad_perm:[1,0,3,2] row_mask:0xf bank_mask:0xf bound_ctrl:1
	v_pk_fma_f32 v[34:35], v[168:169], v[202:203], v[34:35] op_sel_hi:[1,0,1]
	v_add_f32_dpp v33, v33, v33 quad_perm:[2,3,0,1] row_mask:0xf bank_mask:0xf bound_ctrl:1
	v_add_f32_dpp v32, v32, v32 quad_perm:[2,3,0,1] row_mask:0xf bank_mask:0xf bound_ctrl:1
	s_nop 0
	v_add_f32_dpp v33, v33, v33 row_ror:4 row_mask:0xf bank_mask:0xf bound_ctrl:1
	v_add_f32_dpp v166, v32, v32 row_ror:4 row_mask:0xf bank_mask:0xf bound_ctrl:1
	s_nop 0
	v_add_f32_dpp v32, v33, v33 row_ror:8 row_mask:0xf bank_mask:0xf bound_ctrl:1
	v_add_f32_dpp v33, v166, v166 row_ror:8 row_mask:0xf bank_mask:0xf bound_ctrl:1
	v_cndmask_b32_e64 v31, v31, v33, s[16:17]
	v_pk_fma_f32 v[196:197], v[176:177], v[32:33], v[34:35] op_sel_hi:[1,0,1]
	v_pk_fma_f32 v[198:199], v[178:179], v[32:33], v[164:165] op_sel_hi:[1,0,1]
	ds_read_b128 v[32:35], v28 offset:36864
	ds_read_b128 v[164:167], v28 offset:37120
	ds_read_b128 v[168:171], v28 offset:37376
	ds_read_b128 v[172:175], v28 offset:37888
	ds_read_b128 v[176:179], v28 offset:38144
	ds_read_b32 v202, v29 offset:37632
	s_waitcnt lgkmcnt(8)
	v_pk_mul_f32 v[190:191], v[190:191], v[198:199]
	v_pk_mul_f32 v[162:163], v[162:163], v[198:199]
	v_pk_fma_f32 v[188:189], v[188:189], v[196:197], v[190:191]
	v_pk_fma_f32 v[160:161], v[160:161], v[196:197], v[162:163]
	v_pk_mul_f32 v[162:163], v[180:181], v[196:197]
	v_pk_mul_f32 v[180:181], v[182:183], v[198:199]
	v_add_f32_e32 v182, v188, v189
	v_add_f32_e32 v160, v160, v161
	s_waitcnt lgkmcnt(6)
	v_pk_fma_f32 v[180:181], v[186:187], v[200:201], v[180:181] op_sel_hi:[1,0,1]
	v_add_f32_dpp v161, v182, v182 quad_perm:[1,0,3,2] row_mask:0xf bank_mask:0xf bound_ctrl:1
	v_add_f32_dpp v160, v160, v160 quad_perm:[1,0,3,2] row_mask:0xf bank_mask:0xf bound_ctrl:1
	v_pk_fma_f32 v[162:163], v[184:185], v[200:201], v[162:163] op_sel_hi:[1,0,1]
	v_add_f32_dpp v161, v161, v161 quad_perm:[2,3,0,1] row_mask:0xf bank_mask:0xf bound_ctrl:1
	v_add_f32_dpp v160, v160, v160 quad_perm:[2,3,0,1] row_mask:0xf bank_mask:0xf bound_ctrl:1
	s_nop 0
	v_add_f32_dpp v161, v161, v161 row_ror:4 row_mask:0xf bank_mask:0xf bound_ctrl:1
	v_add_f32_dpp v182, v160, v160 row_ror:4 row_mask:0xf bank_mask:0xf bound_ctrl:1
	s_nop 0
	v_add_f32_dpp v160, v161, v161 row_ror:8 row_mask:0xf bank_mask:0xf bound_ctrl:1
	v_add_f32_dpp v161, v182, v182 row_ror:8 row_mask:0xf bank_mask:0xf bound_ctrl:1
	v_cndmask_b32_e64 v31, v31, v161, s[18:19]
	v_pk_fma_f32 v[196:197], v[192:193], v[160:161], v[162:163] op_sel_hi:[1,0,1]
	v_pk_fma_f32 v[198:199], v[194:195], v[160:161], v[180:181] op_sel_hi:[1,0,1]
	ds_read_b128 v[160:163], v28 offset:38400
	ds_read_b128 v[180:183], v28 offset:38656
	ds_read_b128 v[184:187], v28 offset:38912
	ds_read_b128 v[188:191], v28 offset:39424
	ds_read_b128 v[192:195], v28 offset:39680
	ds_read_b32 v200, v29 offset:39168
	s_waitcnt lgkmcnt(8)
	v_pk_mul_f32 v[174:175], v[174:175], v[198:199]
	v_pk_mul_f32 v[26:27], v[26:27], v[198:199]
	v_pk_fma_f32 v[172:173], v[172:173], v[196:197], v[174:175]
	v_pk_fma_f32 v[24:25], v[24:25], v[196:197], v[26:27]
	v_pk_mul_f32 v[26:27], v[164:165], v[196:197]
	v_pk_mul_f32 v[164:165], v[166:167], v[198:199]
	v_add_f32_e32 v166, v172, v173
	v_add_f32_e32 v24, v24, v25
	s_waitcnt lgkmcnt(6)
	v_pk_fma_f32 v[164:165], v[170:171], v[202:203], v[164:165] op_sel_hi:[1,0,1]
	v_add_f32_dpp v25, v166, v166 quad_perm:[1,0,3,2] row_mask:0xf bank_mask:0xf bound_ctrl:1
	v_add_f32_dpp v24, v24, v24 quad_perm:[1,0,3,2] row_mask:0xf bank_mask:0xf bound_ctrl:1
	v_pk_fma_f32 v[26:27], v[168:169], v[202:203], v[26:27] op_sel_hi:[1,0,1]
	v_add_f32_dpp v25, v25, v25 quad_perm:[2,3,0,1] row_mask:0xf bank_mask:0xf bound_ctrl:1
	v_add_f32_dpp v24, v24, v24 quad_perm:[2,3,0,1] row_mask:0xf bank_mask:0xf bound_ctrl:1
	s_nop 0
	v_add_f32_dpp v25, v25, v25 row_ror:4 row_mask:0xf bank_mask:0xf bound_ctrl:1
	v_add_f32_dpp v166, v24, v24 row_ror:4 row_mask:0xf bank_mask:0xf bound_ctrl:1
	s_nop 0
	v_add_f32_dpp v24, v25, v25 row_ror:8 row_mask:0xf bank_mask:0xf bound_ctrl:1
	v_add_f32_dpp v25, v166, v166 row_ror:8 row_mask:0xf bank_mask:0xf bound_ctrl:1
	v_cndmask_b32_e64 v31, v31, v25, s[20:21]
	v_pk_fma_f32 v[196:197], v[176:177], v[24:25], v[26:27] op_sel_hi:[1,0,1]
	v_pk_fma_f32 v[198:199], v[178:179], v[24:25], v[164:165] op_sel_hi:[1,0,1]
	ds_read_b128 v[24:27], v28 offset:39936
	ds_read_b128 v[164:167], v28 offset:40192
	ds_read_b128 v[168:171], v28 offset:40448
	ds_read_b128 v[172:175], v28 offset:40960
	ds_read_b128 v[176:179], v28 offset:41216
	ds_read_b32 v202, v29 offset:40704
	s_waitcnt lgkmcnt(8)
	v_pk_mul_f32 v[190:191], v[190:191], v[198:199]
	v_pk_mul_f32 v[34:35], v[34:35], v[198:199]
	v_pk_fma_f32 v[188:189], v[188:189], v[196:197], v[190:191]
	v_pk_fma_f32 v[32:33], v[32:33], v[196:197], v[34:35]
	v_pk_mul_f32 v[34:35], v[180:181], v[196:197]
	v_pk_mul_f32 v[180:181], v[182:183], v[198:199]
	v_add_f32_e32 v182, v188, v189
	v_add_f32_e32 v32, v32, v33
	s_waitcnt lgkmcnt(6)
; #define LAS __attribute__((address_space(3)))
; __device__ __forceinline__ void rwkv_scan_prompt(const Params& p, LAS unsigned char* lds, int bh, int rq) {
;     ...
;             for (int tk = 0; tk < TC; ++tk) {
;                 f32x4 nr4 = r4, nd4 = d4, nk4 = k4, na4 = a4, nb4 = b4; float nvv = vv;
;                 if (tk < TC - 1) {
;                     const LAS float* o = ob + (tk + 1) * 6 * 64;
;                     nr4 = *(const LAS f32x4*)(o + cg_ * 4); nd4 = *(const LAS f32x4*)(o + 64 + cg_ * 4); nk4 = *(const LAS f32x4*)(o + 128 + cg_ * 4);
;                     na4 = *(const LAS f32x4*)(o + 256 + cg_ * 4); nb4 = *(const LAS f32x4*)(o + 320 + cg_ * 4);
;                     nvv = o[192 + rq * 16 + rloc];
;                 }
;                 __builtin_amdgcn_sched_barrier(0);
;                 typedef float f32x2_ __attribute__((ext_vector_type(2)));
;                 f32x2_ ta = (f32x2_){S[0], S[1]} * (f32x2_){a4[0], a4[1]}; ta = (f32x2_){S[2], S[3]} * (f32x2_){a4[2], a4[3]} + ta;
;                 f32x2_ ty = (f32x2_){S[0], S[1]} * (f32x2_){rp[0], rp[1]}; ty = (f32x2_){S[2], S[3]} * (f32x2_){rp[2], rp[3]} + ty;
;                 const f32x4 T = S * d4 + vv * k4;
;                 float sa = ta[0] + ta[1];
;                 float yp = ty[0] + ty[1];
;                 sa = dpp_add<0xB1>(sa); yp = dpp_add<0xB1>(yp);
;                 sa = dpp_add<0x4E>(sa); yp = dpp_add<0x4E>(yp);
;                 sa = dpp_add<0x124>(sa); yp = dpp_add<0x124>(yp);
;                 sa = dpp_add<0x128>(sa); yp = dpp_add<0x128>(yp);
;                 if (tk > 0) yk[(tk - 1) >> 4] = (cg_ == ((tk - 1) & 15)) ? yp : yk[(tk - 1) >> 4];
;                 S = sa * b4 + T;
;                 rp = r4;
;                 r4 = nr4; d4 = nd4; k4 = nk4; a4 = na4; b4 = nb4; vv = nvv;
;             }
	v_pk_fma_f32 v[180:181], v[186:187], v[200:201], v[180:181] op_sel_hi:[1,0,1]
	v_add_f32_dpp v33, v182, v182 quad_perm:[1,0,3,2] row_mask:0xf bank_mask:0xf bound_ctrl:1
	v_add_f32_dpp v32, v32, v32 quad_perm:[1,0,3,2] row_mask:0xf bank_mask:0xf bound_ctrl:1
	v_pk_fma_f32 v[34:35], v[184:185], v[200:201], v[34:35] op_sel_hi:[1,0,1]
	v_add_f32_dpp v33, v33, v33 quad_perm:[2,3,0,1] row_mask:0xf bank_mask:0xf bound_ctrl:1
	v_add_f32_dpp v32, v32, v32 quad_perm:[2,3,0,1] row_mask:0xf bank_mask:0xf bound_ctrl:1
	s_nop 0
	v_add_f32_dpp v33, v33, v33 row_ror:4 row_mask:0xf bank_mask:0xf bound_ctrl:1
	v_add_f32_dpp v182, v32, v32 row_ror:4 row_mask:0xf bank_mask:0xf bound_ctrl:1
	s_nop 0
	v_add_f32_dpp v32, v33, v33 row_ror:8 row_mask:0xf bank_mask:0xf bound_ctrl:1
	v_add_f32_dpp v33, v182, v182 row_ror:8 row_mask:0xf bank_mask:0xf bound_ctrl:1
	v_cndmask_b32_e64 v31, v31, v33, s[22:23]
	v_pk_fma_f32 v[196:197], v[192:193], v[32:33], v[34:35] op_sel_hi:[1,0,1]
	v_pk_fma_f32 v[198:199], v[194:195], v[32:33], v[180:181] op_sel_hi:[1,0,1]
	ds_read_b128 v[32:35], v28 offset:41472
	ds_read_b128 v[180:183], v28 offset:41728
	ds_read_b128 v[184:187], v28 offset:41984
	ds_read_b128 v[188:191], v28 offset:42496
	ds_read_b128 v[192:195], v28 offset:42752
	ds_read_b32 v200, v29 offset:42240
	s_waitcnt lgkmcnt(8)
	v_pk_mul_f32 v[174:175], v[174:175], v[198:199]
	v_pk_mul_f32 v[162:163], v[162:163], v[198:199]
	v_pk_fma_f32 v[172:173], v[172:173], v[196:197], v[174:175]
	v_pk_fma_f32 v[160:161], v[160:161], v[196:197], v[162:163]
	v_pk_mul_f32 v[162:163], v[164:165], v[196:197]
	v_pk_mul_f32 v[164:165], v[166:167], v[198:199]
	v_add_f32_e32 v166, v172, v173
	v_add_f32_e32 v160, v160, v161
	s_waitcnt lgkmcnt(6)
	v_pk_fma_f32 v[164:165], v[170:171], v[202:203], v[164:165] op_sel_hi:[1,0,1]
	v_add_f32_dpp v161, v166, v166 quad_perm:[1,0,3,2] row_mask:0xf bank_mask:0xf bound_ctrl:1
	v_add_f32_dpp v160, v160, v160 quad_perm:[1,0,3,2] row_mask:0xf bank_mask:0xf bound_ctrl:1
	v_pk_fma_f32 v[162:163], v[168:169], v[202:203], v[162:163] op_sel_hi:[1,0,1]
	v_add_f32_dpp v161, v161, v161 quad_perm:[2,3,0,1] row_mask:0xf bank_mask:0xf bound_ctrl:1
	v_add_f32_dpp v160, v160, v160 quad_perm:[2,3,0,1] row_mask:0xf bank_mask:0xf bound_ctrl:1
	s_nop 0
	v_add_f32_dpp v161, v161, v161 row_ror:4 row_mask:0xf bank_mask:0xf bound_ctrl:1
	v_add_f32_dpp v166, v160, v160 row_ror:4 row_mask:0xf bank_mask:0xf bound_ctrl:1
	s_nop 0
	v_add_f32_dpp v160, v161, v161 row_ror:8 row_mask:0xf bank_mask:0xf bound_ctrl:1
	v_add_f32_dpp v161, v166, v166 row_ror:8 row_mask:0xf bank_mask:0xf bound_ctrl:1
	v_cndmask_b32_e64 v31, v31, v161, s[24:25]
	v_pk_fma_f32 v[196:197], v[176:177], v[160:161], v[162:163] op_sel_hi:[1,0,1]
	v_pk_fma_f32 v[198:199], v[178:179], v[160:161], v[164:165] op_sel_hi:[1,0,1]
	ds_read_b128 v[160:163], v28 offset:43008
	ds_read_b128 v[164:167], v28 offset:43264
	ds_read_b128 v[168:171], v28 offset:43520
	ds_read_b128 v[172:175], v28 offset:44032
	ds_read_b128 v[176:179], v28 offset:44288
	ds_read_b32 v202, v29 offset:43776
	s_waitcnt lgkmcnt(8)
	v_pk_mul_f32 v[190:191], v[190:191], v[198:199]
	v_pk_mul_f32 v[26:27], v[26:27], v[198:199]
	v_pk_fma_f32 v[188:189], v[188:189], v[196:197], v[190:191]
	v_pk_fma_f32 v[24:25], v[24:25], v[196:197], v[26:27]
	v_pk_mul_f32 v[26:27], v[180:181], v[196:197]
	v_pk_mul_f32 v[180:181], v[182:183], v[198:199]
	v_add_f32_e32 v182, v188, v189
	v_add_f32_e32 v24, v24, v25
	s_waitcnt lgkmcnt(6)
	v_pk_fma_f32 v[180:181], v[186:187], v[200:201], v[180:181] op_sel_hi:[1,0,1]
	v_add_f32_dpp v25, v182, v182 quad_perm:[1,0,3,2] row_mask:0xf bank_mask:0xf bound_ctrl:1
	v_add_f32_dpp v24, v24, v24 quad_perm:[1,0,3,2] row_mask:0xf bank_mask:0xf bound_ctrl:1
	v_pk_fma_f32 v[26:27], v[184:185], v[200:201], v[26:27] op_sel_hi:[1,0,1]
	v_add_f32_dpp v25, v25, v25 quad_perm:[2,3,0,1] row_mask:0xf bank_mask:0xf bound_ctrl:1
	v_add_f32_dpp v24, v24, v24 quad_perm:[2,3,0,1] row_mask:0xf bank_mask:0xf bound_ctrl:1
	s_nop 0
	v_add_f32_dpp v25, v25, v25 row_ror:4 row_mask:0xf bank_mask:0xf bound_ctrl:1
	v_add_f32_dpp v182, v24, v24 row_ror:4 row_mask:0xf bank_mask:0xf bound_ctrl:1
	s_nop 0
	v_add_f32_dpp v24, v25, v25 row_ror:8 row_mask:0xf bank_mask:0xf bound_ctrl:1
	v_add_f32_dpp v25, v182, v182 row_ror:8 row_mask:0xf bank_mask:0xf bound_ctrl:1
	v_cndmask_b32_e64 v31, v31, v25, s[26:27]
	v_pk_fma_f32 v[196:197], v[192:193], v[24:25], v[26:27] op_sel_hi:[1,0,1]
	v_pk_fma_f32 v[198:199], v[194:195], v[24:25], v[180:181] op_sel_hi:[1,0,1]
	ds_read_b128 v[24:27], v28 offset:44544
	ds_read_b128 v[180:183], v28 offset:44800
	ds_read_b128 v[184:187], v28 offset:45056
	ds_read_b128 v[188:191], v28 offset:45568
	ds_read_b128 v[192:195], v28 offset:45824
	ds_read_b32 v200, v29 offset:45312
	s_waitcnt lgkmcnt(8)
	v_pk_mul_f32 v[174:175], v[174:175], v[198:199]
	v_pk_mul_f32 v[34:35], v[34:35], v[198:199]
	v_pk_fma_f32 v[172:173], v[172:173], v[196:197], v[174:175]
	v_pk_fma_f32 v[32:33], v[32:33], v[196:197], v[34:35]
	v_pk_mul_f32 v[34:35], v[164:165], v[196:197]
	v_pk_mul_f32 v[164:165], v[166:167], v[198:199]
	v_add_f32_e32 v166, v172, v173
	v_add_f32_e32 v32, v32, v33
	s_waitcnt lgkmcnt(6)
; #define LAS __attribute__((address_space(3)))
; __device__ __forceinline__ void rwkv_scan_prompt(const Params& p, LAS unsigned char* lds, int bh, int rq) {
;     ...
;             for (int tk = 0; tk < TC; ++tk) {
;                 f32x4 nr4 = r4, nd4 = d4, nk4 = k4, na4 = a4, nb4 = b4; float nvv = vv;
;                 if (tk < TC - 1) {
;                     const LAS float* o = ob + (tk + 1) * 6 * 64;
;                     nr4 = *(const LAS f32x4*)(o + cg_ * 4); nd4 = *(const LAS f32x4*)(o + 64 + cg_ * 4); nk4 = *(const LAS f32x4*)(o + 128 + cg_ * 4);
;                     na4 = *(const LAS f32x4*)(o + 256 + cg_ * 4); nb4 = *(const LAS f32x4*)(o + 320 + cg_ * 4);
;                     nvv = o[192 + rq * 16 + rloc];
;                 }
;                 __builtin_amdgcn_sched_barrier(0);
;                 typedef float f32x2_ __attribute__((ext_vector_type(2)));
;                 f32x2_ ta = (f32x2_){S[0], S[1]} * (f32x2_){a4[0], a4[1]}; ta = (f32x2_){S[2], S[3]} * (f32x2_){a4[2], a4[3]} + ta;
;                 f32x2_ ty = (f32x2_){S[0], S[1]} * (f32x2_){rp[0], rp[1]}; ty = (f32x2_){S[2], S[3]} * (f32x2_){rp[2], rp[3]} + ty;
;                 const f32x4 T = S * d4 + vv * k4;
;                 float sa = ta[0] + ta[1];
;                 float yp = ty[0] + ty[1];
;                 sa = dpp_add<0xB1>(sa); yp = dpp_add<0xB1>(yp);
;                 sa = dpp_add<0x4E>(sa); yp = dpp_add<0x4E>(yp);
;                 sa = dpp_add<0x124>(sa); yp = dpp_add<0x124>(yp);
;                 sa = dpp_add<0x128>(sa); yp = dpp_add<0x128>(yp);
;                 if (tk > 0) yk[(tk - 1) >> 4] = (cg_ == ((tk - 1) & 15)) ? yp : yk[(tk - 1) >> 4];
;                 S = sa * b4 + T;
;                 rp = r4;
;                 r4 = nr4; d4 = nd4; k4 = nk4; a4 = na4; b4 = nb4; vv = nvv;
;             }
;             {
;                 float yp = S[0] * rp[0] + S[1] * rp[1] + S[2] * rp[2] + S[3] * rp[3];
;                 yp = row_sum16(yp);
;                 yk[(TC - 1) >> 4] = (cg_ == ((TC - 1) & 15)) ? yp : yk[(TC - 1) >> 4];
;             }
; #pragma unroll
;             for (int j = 0; j < TC / 16; ++j) yk[j] += RKB[buf * TC + j * 16 + cg_] * ob[(j * 16 + cg_) * 6 * 64 + 192 + rq * 16 + rloc];
; #pragma unroll
;             for (int j = 0; j < TC / 16; ++j) YRAW[(size_t)(rowbase + c * TC + j * 16 + cg_) * 512 + h * 64 + rq * 16 + rloc] = yk[j];
	v_pk_fma_f32 v[164:165], v[170:171], v[202:203], v[164:165] op_sel_hi:[1,0,1]
	v_add_f32_dpp v33, v166, v166 quad_perm:[1,0,3,2] row_mask:0xf bank_mask:0xf bound_ctrl:1
	v_add_f32_dpp v32, v32, v32 quad_perm:[1,0,3,2] row_mask:0xf bank_mask:0xf bound_ctrl:1
	v_pk_fma_f32 v[34:35], v[168:169], v[202:203], v[34:35] op_sel_hi:[1,0,1]
	v_add_f32_dpp v33, v33, v33 quad_perm:[2,3,0,1] row_mask:0xf bank_mask:0xf bound_ctrl:1
	v_add_f32_dpp v32, v32, v32 quad_perm:[2,3,0,1] row_mask:0xf bank_mask:0xf bound_ctrl:1
	s_nop 0
	v_add_f32_dpp v33, v33, v33 row_ror:4 row_mask:0xf bank_mask:0xf bound_ctrl:1
	v_add_f32_dpp v166, v32, v32 row_ror:4 row_mask:0xf bank_mask:0xf bound_ctrl:1
	s_nop 0
	v_add_f32_dpp v32, v33, v33 row_ror:8 row_mask:0xf bank_mask:0xf bound_ctrl:1
	v_add_f32_dpp v33, v166, v166 row_ror:8 row_mask:0xf bank_mask:0xf bound_ctrl:1
	v_cndmask_b32_e64 v31, v31, v33, s[28:29]
	v_pk_fma_f32 v[196:197], v[176:177], v[32:33], v[34:35] op_sel_hi:[1,0,1]
	v_pk_fma_f32 v[198:199], v[178:179], v[32:33], v[164:165] op_sel_hi:[1,0,1]
	ds_read_b128 v[32:35], v28 offset:46080
	ds_read_b128 v[164:167], v28 offset:46336
	ds_read_b128 v[168:171], v28 offset:46592
	ds_read_b128 v[172:175], v28 offset:47104
	ds_read_b128 v[176:179], v28 offset:47360
	ds_read_b32 v202, v29 offset:46848
	s_waitcnt lgkmcnt(8)
	v_pk_mul_f32 v[190:191], v[190:191], v[198:199]
	v_pk_mul_f32 v[162:163], v[162:163], v[198:199]
	v_pk_fma_f32 v[188:189], v[188:189], v[196:197], v[190:191]
	v_pk_fma_f32 v[160:161], v[160:161], v[196:197], v[162:163]
	v_pk_mul_f32 v[162:163], v[180:181], v[196:197]
	v_pk_mul_f32 v[180:181], v[182:183], v[198:199]
	v_add_f32_e32 v182, v188, v189
	v_add_f32_e32 v160, v160, v161
	s_waitcnt lgkmcnt(6)
	v_pk_fma_f32 v[180:181], v[186:187], v[200:201], v[180:181] op_sel_hi:[1,0,1]
	v_add_f32_dpp v161, v182, v182 quad_perm:[1,0,3,2] row_mask:0xf bank_mask:0xf bound_ctrl:1
	v_add_f32_dpp v160, v160, v160 quad_perm:[1,0,3,2] row_mask:0xf bank_mask:0xf bound_ctrl:1
	v_pk_fma_f32 v[162:163], v[184:185], v[200:201], v[162:163] op_sel_hi:[1,0,1]
	v_add_f32_dpp v161, v161, v161 quad_perm:[2,3,0,1] row_mask:0xf bank_mask:0xf bound_ctrl:1
	v_add_f32_dpp v160, v160, v160 quad_perm:[2,3,0,1] row_mask:0xf bank_mask:0xf bound_ctrl:1
	s_nop 0
	v_add_f32_dpp v161, v161, v161 row_ror:4 row_mask:0xf bank_mask:0xf bound_ctrl:1
	v_add_f32_dpp v182, v160, v160 row_ror:4 row_mask:0xf bank_mask:0xf bound_ctrl:1
	s_nop 0
	v_add_f32_dpp v160, v161, v161 row_ror:8 row_mask:0xf bank_mask:0xf bound_ctrl:1
	v_add_f32_dpp v161, v182, v182 row_ror:8 row_mask:0xf bank_mask:0xf bound_ctrl:1
	v_cndmask_b32_e64 v31, v31, v161, s[30:31]
	v_pk_fma_f32 v[196:197], v[192:193], v[160:161], v[162:163] op_sel_hi:[1,0,1]
	v_pk_fma_f32 v[198:199], v[194:195], v[160:161], v[180:181] op_sel_hi:[1,0,1]
	ds_read_b128 v[160:163], v28 offset:47616
	ds_read_b128 v[180:183], v28 offset:47872
	ds_read_b128 v[184:187], v28 offset:48128
	ds_read_b128 v[188:191], v28 offset:48640
	ds_read_b128 v[192:195], v28 offset:48896
	ds_read_b32 v28, v29 offset:48384
	s_waitcnt lgkmcnt(8)
	v_pk_mul_f32 v[174:175], v[174:175], v[198:199]
	v_pk_mul_f32 v[26:27], v[26:27], v[198:199]
	v_pk_fma_f32 v[172:173], v[172:173], v[196:197], v[174:175]
	v_pk_fma_f32 v[24:25], v[24:25], v[196:197], v[26:27]
	v_add_f32_e32 v29, v172, v173
	v_add_f32_e32 v24, v24, v25
	v_pk_mul_f32 v[26:27], v[164:165], v[196:197]
	v_add_f32_dpp v25, v29, v29 quad_perm:[1,0,3,2] row_mask:0xf bank_mask:0xf bound_ctrl:1
	v_add_f32_dpp v24, v24, v24 quad_perm:[1,0,3,2] row_mask:0xf bank_mask:0xf bound_ctrl:1
	v_pk_mul_f32 v[164:165], v[166:167], v[198:199]
	v_add_f32_dpp v25, v25, v25 quad_perm:[2,3,0,1] row_mask:0xf bank_mask:0xf bound_ctrl:1
	v_add_f32_dpp v24, v24, v24 quad_perm:[2,3,0,1] row_mask:0xf bank_mask:0xf bound_ctrl:1
	s_waitcnt lgkmcnt(6)
	v_pk_fma_f32 v[164:165], v[170:171], v[202:203], v[164:165] op_sel_hi:[1,0,1]
	v_add_f32_dpp v25, v25, v25 row_ror:4 row_mask:0xf bank_mask:0xf bound_ctrl:1
	v_add_f32_dpp v29, v24, v24 row_ror:4 row_mask:0xf bank_mask:0xf bound_ctrl:1
	v_pk_fma_f32 v[26:27], v[168:169], v[202:203], v[26:27] op_sel_hi:[1,0,1]
	v_add_f32_dpp v24, v25, v25 row_ror:8 row_mask:0xf bank_mask:0xf bound_ctrl:1
	v_add_f32_dpp v25, v29, v29 row_ror:8 row_mask:0xf bank_mask:0xf bound_ctrl:1
	v_cndmask_b32_e64 v29, v31, v25, s[34:35]
	v_pk_fma_f32 v[26:27], v[176:177], v[24:25], v[26:27] op_sel_hi:[1,0,1]
	v_pk_fma_f32 v[24:25], v[178:179], v[24:25], v[164:165] op_sel_hi:[1,0,1]
	s_waitcnt lgkmcnt(2)
	v_pk_mul_f32 v[164:165], v[190:191], v[24:25]
	v_pk_mul_f32 v[34:35], v[34:35], v[24:25]
	v_pk_fma_f32 v[164:165], v[188:189], v[26:27], v[164:165]
	v_pk_fma_f32 v[32:33], v[32:33], v[26:27], v[34:35]
	v_pk_mul_f32 v[26:27], v[180:181], v[26:27]
	v_pk_mul_f32 v[24:25], v[182:183], v[24:25]
	s_waitcnt lgkmcnt(0)
	v_pk_fma_f32 v[34:35], v[184:185], v[28:29], v[26:27] op_sel_hi:[1,0,1]
	v_add_f32_e32 v26, v164, v165
	v_add_f32_e32 v27, v32, v33
	v_pk_fma_f32 v[24:25], v[186:187], v[28:29], v[24:25] op_sel_hi:[1,0,1]
	v_add_f32_dpp v26, v26, v26 quad_perm:[1,0,3,2] row_mask:0xf bank_mask:0xf bound_ctrl:1
	v_add_f32_dpp v27, v27, v27 quad_perm:[1,0,3,2] row_mask:0xf bank_mask:0xf bound_ctrl:1
	s_lshl_b32 s79, s94, 2
	v_add_f32_dpp v26, v26, v26 quad_perm:[2,3,0,1] row_mask:0xf bank_mask:0xf bound_ctrl:1
	v_add_f32_dpp v27, v27, v27 quad_perm:[2,3,0,1] row_mask:0xf bank_mask:0xf bound_ctrl:1
	s_add_i32 s79, s79, s78
	v_add_f32_dpp v26, v26, v26 row_ror:4 row_mask:0xf bank_mask:0xf bound_ctrl:1
	v_add_f32_dpp v27, v27, v27 row_ror:4 row_mask:0xf bank_mask:0xf bound_ctrl:1
	v_add3_u32 v32, s79, v135, v84
	v_add_f32_dpp v28, v26, v26 row_ror:8 row_mask:0xf bank_mask:0xf bound_ctrl:1
	v_add_f32_dpp v26, v27, v27 row_ror:8 row_mask:0xf bank_mask:0xf bound_ctrl:1
	v_cndmask_b32_e64 v31, v29, v26, s[36:37]
	v_pk_fma_f32 v[26:27], v[194:195], v[28:29], v[24:25] op_sel_hi:[1,0,1]
	v_pk_fma_f32 v[24:25], v[192:193], v[28:29], v[34:35] op_sel_hi:[1,0,1]
	ds_read2st64_b32 v[32:33], v32 offset0:3 offset1:99
	v_mul_f32_e32 v28, v161, v25
	v_fmac_f32_e32 v28, v160, v24
	v_fmac_f32_e32 v28, v162, v26
	v_fmac_f32_e32 v28, v163, v27
	s_nop 1
	v_add_f32_dpp v34, v28, v28 quad_perm:[1,0,3,2] row_mask:0xf bank_mask:0xf bound_ctrl:1
	v_lshl_add_u32 v28, s95, 7, v126
	ds_read2_b32 v[28:29], v28 offset1:16
	v_add_f32_dpp v34, v34, v34 quad_perm:[2,3,0,1] row_mask:0xf bank_mask:0xf bound_ctrl:1
	s_waitcnt lgkmcnt(0)
	v_fmac_f32_e32 v30, v28, v32
	v_add_f32_dpp v34, v34, v34 row_ror:4 row_mask:0xf bank_mask:0xf bound_ctrl:1
	v_add_u32_e32 v28, s0, v159
	s_nop 0
	v_add_f32_dpp v34, v34, v34 row_ror:8 row_mask:0xf bank_mask:0xf bound_ctrl:1
	v_cndmask_b32_e64 v31, v31, v34, s[4:5]
	v_fmac_f32_e32 v31, v29, v33
	v_ashrrev_i32_e32 v29, 31, v28
	v_lshlrev_b64 v[32:33], 11, v[28:29]
	v_add_u32_e32 v28, 16, v28
	v_ashrrev_i32_e32 v29, 31, v28
	v_lshlrev_b64 v[28:29], 11, v[28:29]
	v_lshl_add_u64 v[32:33], v[88:89], 0, v[32:33]
	v_lshl_add_u64 v[28:29], v[88:89], 0, v[28:29]
	s_cmp_lg_u32 s100, 0
	s_cbranch_scc1 .Lps_s_ok
; __device__ __forceinline__ void rwkv_scan_prompt(const Params& p, LAS unsigned char* lds, int bh, int rq) {
;     ...
;             for (int j = 0; j < TC / 16; ++j) YRAW[(size_t)(rowbase + c * TC + j * 16 + cg_) * 512 + h * 64 + rq * 16 + rloc] = yk[j];
	v_mov_b32_e32 v204, 0x1b6f980
.Lps_s_poll:
	global_load_dword v205, v204, s[82:83] sc1
	s_waitcnt vmcnt(0)
	v_readfirstlane_b32 s101, v205
	s_cmpk_lt_u32 s101, 0x100
	s_cbranch_scc0 .Lps_s_done
	s_sleep 1
	s_branch .Lps_s_poll
.Lps_s_done:
	s_mov_b32 s100, 1
.Lps_s_ok:
	global_store_dword v[32:33], v30, off sc0 sc1
	global_store_dword v[28:29], v31, off sc0 sc1
